# E21 + in-proj epilogue (layers 1,3): the 8 per-row rs[] loads for the fused pre-norm scale issued together up front instead of one load + vmcnt(0) store drain per row
# speedup vs baseline: 1.0080x; 1.0080x over previous
; #define PG8_STAGE(bufoff, gbase, voff) do { _Pragma("unroll") for (int _i = 0; _i < 2; ++_i) \
;     __builtin_amdgcn_global_load_lds((const unsigned*)((const char*)(gbase) + (voff)[_i]), (LAS unsigned*)(lds + (bufoff) + ldsw + _i * 8192), 16, 0, 0); } while (0)
; #define PG8_LDA(dst, b, h) do { _Pragma("unroll") for (int m = 0; m < 4; ++m) _Pragma("unroll") for (int k = 0; k < 2; ++k) dst[m][k] = *(const LAS bf16x8*)(lds + PG8_SA(b, h) + aoff + m * 2048 + k * 1024); } while (0)
; #define PG8_LDB(dst, b, h) do { _Pragma("unroll") for (int n = 0; n < 2; ++n) _Pragma("unroll") for (int k = 0; k < 2; ++k) dst[n][k] = *(const LAS bf16x8*)(lds + PG8_SB(b, h) + boff + n * 2048 + k * 1024); } while (0)
; #define PG8_MMA(ai, bj, At, Bt) do { __builtin_amdgcn_s_setprio(1); _Pragma("unroll") for (int m = 0; m < 4; ++m) _Pragma("unroll") for (int n = 0; n < 2; ++n) _Pragma("unroll") for (int k = 0; k < 2; ++k) \
;     acc[ai][bj][m][n] = __builtin_amdgcn_mfma_f32_16x16x32_bf16(Bt[n][k], At[m][k], acc[ai][bj][m][n], 0, 0, 0); __builtin_amdgcn_s_setprio(0); } while (0)
; #define PG8_WAIT_L(n) asm volatile("s_waitcnt lgkmcnt(" #n ")" ::: "memory")
; #define PG8_BAR __builtin_amdgcn_s_barrier()
; #define PG8_SCHED __builtin_amdgcn_sched_barrier(0)
; template <class Epi>
; DI void gemm_phase(LAS unsigned char* lds, const Gemm g, const StaticOrder& S, const Epi& E) {
;     ...
;       PG8_LDB(B0, 0, 0); PG8_SCHED; PG8_LDA(At, 0, 0); PG8_STAGE(PG8_SA(1, 1), a1 + hstep, voffA);
;       PG8_WAIT_L(8); PG8_BAR; PG8_WAIT_L(0); PG8_MMA(0, 0, At, B0); PG8_BAR; PG8_SCHED;
;       PG8_LDB(B1, 0, 1); PG8_STAGE(PG8_SB(0, 0), b2, voffB);
;       PG8_BAR; PG8_WAIT_L(0); PG8_MMA(0, 1, At, B1); PG8_BAR;
;       PG8_LDA(At, 0, 1); PG8_STAGE(PG8_SA(0, 0), a2, voffA);
;       PG8_BAR; PG8_WAIT_L(0); PG8_MMA(1, 0, At, B0); PG8_BAR; PG8_SCHED;
.LBB0_449:
	ds_read_b128 v[144:147], v151
	ds_read_b128 v[156:159], v151 offset:1024
	ds_read_b128 v[160:163], v151 offset:2048
	ds_read_b128 v[164:167], v151 offset:3072
	s_add_u32 s30, s6, 0xfff80080
	s_addc_u32 s31, s7, -1
	s_cmp_eq_u32 s58, 28
	s_cselect_b32 s35, s23, s31
	s_cselect_b32 s34, s54, s30
	s_cselect_b32 s31, s21, s57
	s_cselect_b32 s30, s55, s56
	v_lshl_add_u64 v[200:201], s[6:7], 0, v[138:139]
	s_add_i32 m0, s29, 0xc000
	ds_read_b128 v[168:171], v152
	ds_read_b128 v[172:175], v152 offset:1024
	ds_read_b128 v[176:179], v152 offset:2048
	ds_read_b128 v[180:183], v152 offset:3072
	ds_read_b128 v[184:187], v152 offset:4096
	ds_read_b128 v[188:191], v152 offset:5120
	ds_read_b128 v[192:195], v152 offset:6144
	ds_read_b128 v[196:199], v152 offset:7168
	global_load_lds_dwordx4 v[200:201], off
	v_lshl_add_u64 v[200:201], s[6:7], 0, v[136:137]
	s_add_i32 m0, s29, 0xe000
	s_nop 0
	global_load_lds_dwordx4 v[200:201], off
	s_waitcnt lgkmcnt(8)
	s_barrier
	s_waitcnt lgkmcnt(0)
	s_setprio 1
	s_waitcnt lgkmcnt(0)
	v_mfma_f32_16x16x32_bf16 v[124:127], v[144:147], v[168:171], v[124:127]
	v_mfma_f32_16x16x32_bf16 v[120:123], v[160:163], v[168:171], v[120:123]
	v_mfma_f32_16x16x32_bf16 v[108:111], v[144:147], v[176:179], v[108:111]
	v_mfma_f32_16x16x32_bf16 v[104:107], v[160:163], v[176:179], v[104:107]
	v_mfma_f32_16x16x32_bf16 v[92:95], v[144:147], v[184:187], v[92:95]
	v_mfma_f32_16x16x32_bf16 v[88:91], v[160:163], v[184:187], v[88:91]
	v_mfma_f32_16x16x32_bf16 v[76:79], v[144:147], v[192:195], v[76:79]
	v_mfma_f32_16x16x32_bf16 v[72:75], v[160:163], v[192:195], v[72:75]
	v_mfma_f32_16x16x32_bf16 v[124:127], v[156:159], v[172:175], v[124:127]
	v_mfma_f32_16x16x32_bf16 v[120:123], v[164:167], v[172:175], v[120:123]
	v_mfma_f32_16x16x32_bf16 v[108:111], v[156:159], v[180:183], v[108:111]
	v_mfma_f32_16x16x32_bf16 v[104:107], v[164:167], v[180:183], v[104:107]
	v_mfma_f32_16x16x32_bf16 v[92:95], v[156:159], v[188:191], v[92:95]
	v_mfma_f32_16x16x32_bf16 v[88:91], v[164:167], v[188:191], v[88:91]
	v_mfma_f32_16x16x32_bf16 v[76:79], v[156:159], v[196:199], v[76:79]
	v_mfma_f32_16x16x32_bf16 v[72:75], v[164:167], v[196:199], v[72:75]
	s_setprio 0
	s_barrier
	s_add_i32 s59, s46, s36
	v_lshl_add_u64 v[218:219], s[30:31], 0, v[132:133]
	s_mov_b32 m0, s59
	ds_read_b128 v[200:203], v153
	ds_read_b128 v[204:207], v153 offset:1024
	ds_read_b128 v[210:213], v153 offset:2048
	ds_read_b128 v[214:217], v153 offset:3072
	global_load_lds_dwordx4 v[218:219], off
	v_lshl_add_u64 v[220:221], s[30:31], 0, v[128:129]
	s_add_i32 m0, s59, 0x2000
	s_nop 0
	global_load_lds_dwordx4 v[220:221], off
	s_barrier
	s_waitcnt lgkmcnt(0)
	s_setprio 1
	s_waitcnt lgkmcnt(0)
	v_mfma_f32_16x16x32_bf16 v[116:119], v[200:203], v[168:171], v[116:119]
	v_mfma_f32_16x16x32_bf16 v[112:115], v[210:213], v[168:171], v[112:115]
	v_mfma_f32_16x16x32_bf16 v[100:103], v[200:203], v[176:179], v[100:103]
	v_mfma_f32_16x16x32_bf16 v[96:99], v[210:213], v[176:179], v[96:99]
	v_mfma_f32_16x16x32_bf16 v[84:87], v[200:203], v[184:187], v[84:87]
	v_mfma_f32_16x16x32_bf16 v[80:83], v[210:213], v[184:187], v[80:83]
	v_mfma_f32_16x16x32_bf16 v[68:71], v[200:203], v[192:195], v[68:71]
	v_mfma_f32_16x16x32_bf16 v[64:67], v[210:213], v[192:195], v[64:67]
	v_mfma_f32_16x16x32_bf16 v[116:119], v[204:207], v[172:175], v[116:119]
	v_mfma_f32_16x16x32_bf16 v[112:115], v[214:217], v[172:175], v[112:115]
	v_mfma_f32_16x16x32_bf16 v[100:103], v[204:207], v[180:183], v[100:103]
	v_mfma_f32_16x16x32_bf16 v[96:99], v[214:217], v[180:183], v[96:99]
	v_mfma_f32_16x16x32_bf16 v[84:87], v[204:207], v[188:191], v[84:87]
	v_mfma_f32_16x16x32_bf16 v[80:83], v[214:217], v[188:191], v[80:83]
	v_mfma_f32_16x16x32_bf16 v[68:71], v[204:207], v[196:199], v[68:71]
	v_mfma_f32_16x16x32_bf16 v[64:67], v[214:217], v[196:199], v[64:67]
	s_setprio 0
	s_mov_b32 m0, s29
	v_lshl_add_u64 v[222:223], s[34:35], 0, v[134:135]
	s_barrier
	ds_read_b128 v[168:171], v152 offset:16384
	ds_read_b128 v[172:175], v152 offset:17408
	ds_read_b128 v[176:179], v152 offset:18432
	ds_read_b128 v[180:183], v152 offset:19456
	ds_read_b128 v[184:187], v152 offset:20480
	ds_read_b128 v[188:191], v152 offset:21504
	ds_read_b128 v[192:195], v152 offset:22528
	ds_read_b128 v[196:199], v152 offset:23552
	global_load_lds_dwordx4 v[222:223], off
	v_lshl_add_u64 v[224:225], s[34:35], 0, v[130:131]
	s_mov_b32 m0, s39
	s_nop 0
	global_load_lds_dwordx4 v[224:225], off
	s_barrier
	s_waitcnt lgkmcnt(0)
	s_setprio 1
	s_waitcnt lgkmcnt(0)
	v_mfma_f32_16x16x32_bf16 v[60:63], v[144:147], v[168:171], v[60:63]
	v_mfma_f32_16x16x32_bf16 v[56:59], v[160:163], v[168:171], v[56:59]
	v_mfma_f32_16x16x32_bf16 v[44:47], v[144:147], v[176:179], v[44:47]
	v_mfma_f32_16x16x32_bf16 v[40:43], v[160:163], v[176:179], v[40:43]
	v_mfma_f32_16x16x32_bf16 v[28:31], v[144:147], v[184:187], v[28:31]
	v_mfma_f32_16x16x32_bf16 v[24:27], v[160:163], v[184:187], v[24:27]
	v_mfma_f32_16x16x32_bf16 v[12:15], v[144:147], v[192:195], v[12:15]
	v_mfma_f32_16x16x32_bf16 v[8:11], v[160:163], v[192:195], v[8:11]
	v_mfma_f32_16x16x32_bf16 v[60:63], v[156:159], v[172:175], v[60:63]
	v_mfma_f32_16x16x32_bf16 v[56:59], v[164:167], v[172:175], v[56:59]
	v_mfma_f32_16x16x32_bf16 v[44:47], v[156:159], v[180:183], v[44:47]
	v_mfma_f32_16x16x32_bf16 v[40:43], v[164:167], v[180:183], v[40:43]
	v_mfma_f32_16x16x32_bf16 v[28:31], v[156:159], v[188:191], v[28:31]
	v_mfma_f32_16x16x32_bf16 v[24:27], v[164:167], v[188:191], v[24:27]
	v_mfma_f32_16x16x32_bf16 v[12:15], v[156:159], v[196:199], v[12:15]
	v_mfma_f32_16x16x32_bf16 v[8:11], v[164:167], v[196:199], v[8:11]
	s_setprio 0
	s_barrier
; #define PG8_STAGE(bufoff, gbase, voff) do { _Pragma("unroll") for (int _i = 0; _i < 2; ++_i) \
;     __builtin_amdgcn_global_load_lds((const unsigned*)((const char*)(gbase) + (voff)[_i]), (LAS unsigned*)(lds + (bufoff) + ldsw + _i * 8192), 16, 0, 0); } while (0)
; #define PG8_LDA(dst, b, h) do { _Pragma("unroll") for (int m = 0; m < 4; ++m) _Pragma("unroll") for (int k = 0; k < 2; ++k) dst[m][k] = *(const LAS bf16x8*)(lds + PG8_SA(b, h) + aoff + m * 2048 + k * 1024); } while (0)
; #define PG8_LDB(dst, b, h) do { _Pragma("unroll") for (int n = 0; n < 2; ++n) _Pragma("unroll") for (int k = 0; k < 2; ++k) dst[n][k] = *(const LAS bf16x8*)(lds + PG8_SB(b, h) + boff + n * 2048 + k * 1024); } while (0)
; #define PG8_MMA(ai, bj, At, Bt) do { __builtin_amdgcn_s_setprio(1); _Pragma("unroll") for (int m = 0; m < 4; ++m) _Pragma("unroll") for (int n = 0; n < 2; ++n) _Pragma("unroll") for (int k = 0; k < 2; ++k) \
;     acc[ai][bj][m][n] = __builtin_amdgcn_mfma_f32_16x16x32_bf16(Bt[n][k], At[m][k], acc[ai][bj][m][n], 0, 0, 0); __builtin_amdgcn_s_setprio(0); } while (0)
; #define PG8_WAIT_V(n) asm volatile("s_waitcnt vmcnt(" #n ")" ::: "memory")
; #define PG8_WAIT_L(n) asm volatile("s_waitcnt lgkmcnt(" #n ")" ::: "memory")
; #define PG8_BAR __builtin_amdgcn_s_barrier()
; #define PG8_SCHED __builtin_amdgcn_sched_barrier(0)
; template <class Epi>
; DI void gemm_phase(LAS unsigned char* lds, const Gemm g, const StaticOrder& S, const Epi& E) {
;     ...
;       PG8_STAGE(PG8_SB(0, 1), b2 + hstep, voffB);
;       PG8_WAIT_V(6); PG8_BAR; PG8_MMA(1, 1, At, B1); PG8_BAR;
;       PG8_LDB(B0, 1, 0); PG8_SCHED; PG8_LDA(At, 1, 0); PG8_STAGE(PG8_SA(0, 1), a2 + hstep, voffA);
;       PG8_WAIT_L(8); PG8_BAR; PG8_WAIT_L(0); PG8_MMA(0, 0, At, B0); PG8_BAR; PG8_SCHED;
;       PG8_LDB(B1, 1, 1); PG8_STAGE(PG8_SB(1, 0), b3, voffB);
;       PG8_BAR; PG8_WAIT_L(0); PG8_MMA(0, 1, At, B1); PG8_BAR;
;       PG8_LDA(At, 1, 1); PG8_STAGE(PG8_SA(1, 0), a3, voffA);
;       PG8_BAR; PG8_WAIT_L(0); PG8_MMA(1, 0, At, B0); PG8_BAR; PG8_SCHED;
	s_add_u32 s64, s30, 0x80000
	s_addc_u32 s65, s31, 0
	s_add_i32 s59, s47, s36
	v_lshl_add_u64 v[144:145], s[64:65], 0, v[132:133]
	s_mov_b32 m0, s59
	s_nop 0
	global_load_lds_dwordx4 v[144:145], off
	v_lshl_add_u64 v[144:145], s[64:65], 0, v[128:129]
	s_add_i32 m0, s59, 0x2000
	s_nop 0
	global_load_lds_dwordx4 v[144:145], off
	s_waitcnt vmcnt(6)
	s_barrier
	s_setprio 1
	v_mfma_f32_16x16x32_bf16 v[52:55], v[200:203], v[168:171], v[52:55]
	v_mfma_f32_16x16x32_bf16 v[48:51], v[210:213], v[168:171], v[48:51]
	v_mfma_f32_16x16x32_bf16 v[36:39], v[200:203], v[176:179], v[36:39]
	v_mfma_f32_16x16x32_bf16 v[32:35], v[210:213], v[176:179], v[32:35]
	v_mfma_f32_16x16x32_bf16 v[20:23], v[200:203], v[184:187], v[20:23]
	v_mfma_f32_16x16x32_bf16 v[16:19], v[210:213], v[184:187], v[16:19]
	v_mfma_f32_16x16x32_bf16 v[4:7], v[200:203], v[192:195], v[4:7]
	v_mfma_f32_16x16x32_bf16 v[0:3], v[210:213], v[192:195], v[0:3]
	v_mfma_f32_16x16x32_bf16 v[52:55], v[204:207], v[172:175], v[52:55]
	v_mfma_f32_16x16x32_bf16 v[48:51], v[214:217], v[172:175], v[48:51]
	v_mfma_f32_16x16x32_bf16 v[36:39], v[204:207], v[180:183], v[36:39]
	v_mfma_f32_16x16x32_bf16 v[32:35], v[214:217], v[180:183], v[32:35]
	v_mfma_f32_16x16x32_bf16 v[20:23], v[204:207], v[188:191], v[20:23]
	v_mfma_f32_16x16x32_bf16 v[16:19], v[214:217], v[188:191], v[16:19]
	v_mfma_f32_16x16x32_bf16 v[4:7], v[204:207], v[196:199], v[4:7]
	v_mfma_f32_16x16x32_bf16 v[0:3], v[214:217], v[196:199], v[0:3]
	s_setprio 0
	s_add_i32 s59, 0, 0x18000
	v_add_u32_e32 v155, s59, v149
	s_barrier
	ds_read_b128 v[144:147], v155
	ds_read_b128 v[156:159], v155 offset:1024
	ds_read_b128 v[160:163], v155 offset:2048
	ds_read_b128 v[164:167], v155 offset:3072
	s_add_u32 s34, s34, 0x80000
	s_addc_u32 s35, s35, 0
	s_mov_b32 m0, s40
	v_lshl_add_u64 v[200:201], s[34:35], 0, v[134:135]
	ds_read_b128 v[168:171], v152 offset:32768
	ds_read_b128 v[172:175], v152 offset:33792
	ds_read_b128 v[176:179], v152 offset:34816
	ds_read_b128 v[180:183], v152 offset:35840
	ds_read_b128 v[184:187], v152 offset:36864
	ds_read_b128 v[188:191], v152 offset:37888
	ds_read_b128 v[192:195], v152 offset:38912
	ds_read_b128 v[196:199], v152 offset:39936
	global_load_lds_dwordx4 v[200:201], off
	v_lshl_add_u64 v[200:201], s[34:35], 0, v[130:131]
	s_mov_b32 m0, s41
	s_nop 0
	global_load_lds_dwordx4 v[200:201], off
	s_waitcnt lgkmcnt(8)
	s_barrier
	s_waitcnt lgkmcnt(0)
	s_setprio 1
	s_waitcnt lgkmcnt(0)
	v_mfma_f32_16x16x32_bf16 v[124:127], v[144:147], v[168:171], v[124:127]
	v_mfma_f32_16x16x32_bf16 v[120:123], v[160:163], v[168:171], v[120:123]
	v_mfma_f32_16x16x32_bf16 v[108:111], v[144:147], v[176:179], v[108:111]
	v_mfma_f32_16x16x32_bf16 v[104:107], v[160:163], v[176:179], v[104:107]
	v_mfma_f32_16x16x32_bf16 v[92:95], v[144:147], v[184:187], v[92:95]
	v_mfma_f32_16x16x32_bf16 v[88:91], v[160:163], v[184:187], v[88:91]
	v_mfma_f32_16x16x32_bf16 v[76:79], v[144:147], v[192:195], v[76:79]
	v_mfma_f32_16x16x32_bf16 v[72:75], v[160:163], v[192:195], v[72:75]
	v_mfma_f32_16x16x32_bf16 v[124:127], v[156:159], v[172:175], v[124:127]
	v_mfma_f32_16x16x32_bf16 v[120:123], v[164:167], v[172:175], v[120:123]
	v_mfma_f32_16x16x32_bf16 v[108:111], v[156:159], v[180:183], v[108:111]
	v_mfma_f32_16x16x32_bf16 v[104:107], v[164:167], v[180:183], v[104:107]
	v_mfma_f32_16x16x32_bf16 v[92:95], v[156:159], v[188:191], v[92:95]
	v_mfma_f32_16x16x32_bf16 v[88:91], v[164:167], v[188:191], v[88:91]
	v_mfma_f32_16x16x32_bf16 v[76:79], v[156:159], v[196:199], v[76:79]
	v_mfma_f32_16x16x32_bf16 v[72:75], v[164:167], v[196:199], v[72:75]
	s_setprio 0
	s_barrier
	s_add_i32 s34, 0, 0x1c000
	s_add_i32 s35, s59, s36
	v_add_u32_e32 v155, s34, v149
	v_lshl_add_u64 v[218:219], v[218:219], 0, s[10:11]
	s_mov_b32 m0, s35
	ds_read_b128 v[200:203], v155
	ds_read_b128 v[204:207], v155 offset:1024
	ds_read_b128 v[210:213], v155 offset:2048
	ds_read_b128 v[214:217], v155 offset:3072
	global_load_lds_dwordx4 v[218:219], off
	v_lshl_add_u64 v[218:219], v[220:221], 0, s[10:11]
	s_add_i32 m0, s35, 0x2000
	s_nop 0
	global_load_lds_dwordx4 v[218:219], off
	s_barrier
	s_waitcnt lgkmcnt(0)
	s_setprio 1
	s_waitcnt lgkmcnt(0)
	v_mfma_f32_16x16x32_bf16 v[116:119], v[200:203], v[168:171], v[116:119]
	v_mfma_f32_16x16x32_bf16 v[112:115], v[210:213], v[168:171], v[112:115]
	v_mfma_f32_16x16x32_bf16 v[100:103], v[200:203], v[176:179], v[100:103]
	v_mfma_f32_16x16x32_bf16 v[96:99], v[210:213], v[176:179], v[96:99]
	v_mfma_f32_16x16x32_bf16 v[84:87], v[200:203], v[184:187], v[84:87]
	v_mfma_f32_16x16x32_bf16 v[80:83], v[210:213], v[184:187], v[80:83]
	v_mfma_f32_16x16x32_bf16 v[68:71], v[200:203], v[192:195], v[68:71]
	v_mfma_f32_16x16x32_bf16 v[64:67], v[210:213], v[192:195], v[64:67]
	v_mfma_f32_16x16x32_bf16 v[116:119], v[204:207], v[172:175], v[116:119]
	v_mfma_f32_16x16x32_bf16 v[112:115], v[214:217], v[172:175], v[112:115]
	v_mfma_f32_16x16x32_bf16 v[100:103], v[204:207], v[180:183], v[100:103]
	v_mfma_f32_16x16x32_bf16 v[96:99], v[214:217], v[180:183], v[96:99]
	v_mfma_f32_16x16x32_bf16 v[84:87], v[204:207], v[188:191], v[84:87]
	v_mfma_f32_16x16x32_bf16 v[80:83], v[214:217], v[188:191], v[80:83]
	v_mfma_f32_16x16x32_bf16 v[68:71], v[204:207], v[196:199], v[68:71]
	v_mfma_f32_16x16x32_bf16 v[64:67], v[214:217], v[196:199], v[64:67]
	s_setprio 0
	s_mov_b32 m0, s43
	v_lshl_add_u64 v[218:219], v[222:223], 0, s[10:11]
	s_barrier
	ds_read_b128 v[168:171], v152 offset:49152
	ds_read_b128 v[172:175], v152 offset:50176
	ds_read_b128 v[176:179], v152 offset:51200
	ds_read_b128 v[180:183], v152 offset:52224
	ds_read_b128 v[184:187], v152 offset:53248
	ds_read_b128 v[188:191], v152 offset:54272
	ds_read_b128 v[192:195], v152 offset:55296
	ds_read_b128 v[196:199], v152 offset:56320
	global_load_lds_dwordx4 v[218:219], off
	v_lshl_add_u64 v[218:219], v[224:225], 0, s[10:11]
	s_mov_b32 m0, s44
	s_nop 0
	global_load_lds_dwordx4 v[218:219], off
	s_barrier
; DI u32 pack2(float a, float b) { f32v2 v = {a, b}; return __builtin_bit_cast(u32, __builtin_convertvector(v, bf16v2)); }
; #define PG8_STAGE(bufoff, gbase, voff) do { _Pragma("unroll") for (int _i = 0; _i < 2; ++_i) \
;     __builtin_amdgcn_global_load_lds((const unsigned*)((const char*)(gbase) + (voff)[_i]), (LAS unsigned*)(lds + (bufoff) + ldsw + _i * 8192), 16, 0, 0); } while (0)
; #define PG8_MMA(ai, bj, At, Bt) do { __builtin_amdgcn_s_setprio(1); _Pragma("unroll") for (int m = 0; m < 4; ++m) _Pragma("unroll") for (int n = 0; n < 2; ++n) _Pragma("unroll") for (int k = 0; k < 2; ++k) \
;     acc[ai][bj][m][n] = __builtin_amdgcn_mfma_f32_16x16x32_bf16(Bt[n][k], At[m][k], acc[ai][bj][m][n], 0, 0, 0); __builtin_amdgcn_s_setprio(0); } while (0)
; #define PG8_WAIT_V(n) asm volatile("s_waitcnt vmcnt(" #n ")" ::: "memory")
; #define PG8_WAIT_L(n) asm volatile("s_waitcnt lgkmcnt(" #n ")" ::: "memory")
; #define PG8_BAR __builtin_amdgcn_s_barrier()
; #define PG8_SCHED __builtin_amdgcn_sched_barrier(0)
; template <class Epi>
; DI void gemm_phase(LAS unsigned char* lds, const Gemm g, const StaticOrder& S, const Epi& E) {
;     ...
;       PG8_BAR; PG8_WAIT_L(0); PG8_MMA(1, 0, At, B0); PG8_BAR; PG8_SCHED;
;       PG8_STAGE(PG8_SB(1, 1), b3 + hstep, voffB);
;       PG8_WAIT_V(6); PG8_BAR; PG8_MMA(1, 1, At, B1); PG8_BAR;
;     }
;   DI void operator()(const f32x4 (&acc)[2][2][4][2], const Unit& u, int wr, int wc, int fr, int fq) const {
;     const int row0 = u.pm * BM + wr * 64 + fr, colt = u.pn * BM, col0 = colt + wc * 32 + 8 * fq;
;     const bool kv = (mode == 1) && colt >= 2048 && colt < 6144;
;     const int sec = colt >= 4096 ? 1 : 0;
; #pragma unroll
;     for (int ai = 0; ai < 2; ++ai)
; #pragma unroll
;       for (int m = 0; m < 4; ++m) {
;         const int row = row0 + ai * HALF + m * 16;
;         u16* rowp = O + (size_t)row * ldc + col0;
;         const float rr = rs ? rsqrtf(rs[row] * (1.f / 2048.f) + 1e-6f) : 1.f;
; #pragma unroll
;         for (int bj = 0; bj < 2; ++bj) {
;           const f32x4 v0 = acc[ai][bj][m][0] * rr, v1 = acc[ai][bj][m][1] * rr;
;           u32x4 w = {pack2(v0[0], v0[1]), pack2(v0[2], v0[3]), pack2(v1[0], v1[1]), pack2(v1[2], v1[3])};
;           *reinterpret_cast<u32x4*>(rowp + bj * HALF) = w;
	s_waitcnt lgkmcnt(0)
	s_setprio 1
	s_waitcnt lgkmcnt(0)
	v_mfma_f32_16x16x32_bf16 v[60:63], v[144:147], v[168:171], v[60:63]
	v_mfma_f32_16x16x32_bf16 v[56:59], v[160:163], v[168:171], v[56:59]
	v_mfma_f32_16x16x32_bf16 v[44:47], v[144:147], v[176:179], v[44:47]
	v_mfma_f32_16x16x32_bf16 v[40:43], v[160:163], v[176:179], v[40:43]
	v_mfma_f32_16x16x32_bf16 v[28:31], v[144:147], v[184:187], v[28:31]
	v_mfma_f32_16x16x32_bf16 v[24:27], v[160:163], v[184:187], v[24:27]
	v_mfma_f32_16x16x32_bf16 v[12:15], v[144:147], v[192:195], v[12:15]
	v_mfma_f32_16x16x32_bf16 v[8:11], v[160:163], v[192:195], v[8:11]
	v_mfma_f32_16x16x32_bf16 v[60:63], v[156:159], v[172:175], v[60:63]
	v_mfma_f32_16x16x32_bf16 v[56:59], v[164:167], v[172:175], v[56:59]
	v_mfma_f32_16x16x32_bf16 v[44:47], v[156:159], v[180:183], v[44:47]
	v_mfma_f32_16x16x32_bf16 v[40:43], v[164:167], v[180:183], v[40:43]
	v_mfma_f32_16x16x32_bf16 v[28:31], v[156:159], v[188:191], v[28:31]
	v_mfma_f32_16x16x32_bf16 v[24:27], v[164:167], v[188:191], v[24:27]
	v_mfma_f32_16x16x32_bf16 v[12:15], v[156:159], v[196:199], v[12:15]
	v_mfma_f32_16x16x32_bf16 v[8:11], v[164:167], v[196:199], v[8:11]
	s_setprio 0
	s_barrier
	s_add_u32 s30, s30, 0x80080
	s_addc_u32 s31, s31, 0
	s_add_i32 s34, s34, s36
	v_lshl_add_u64 v[144:145], s[30:31], 0, v[132:133]
	s_mov_b32 m0, s34
	s_nop 0
	global_load_lds_dwordx4 v[144:145], off
	v_lshl_add_u64 v[144:145], s[30:31], 0, v[128:129]
	s_add_i32 m0, s34, 0x2000
	s_nop 0
	global_load_lds_dwordx4 v[144:145], off
	s_waitcnt vmcnt(6)
	s_barrier
	s_setprio 1
	v_mfma_f32_16x16x32_bf16 v[52:55], v[200:203], v[168:171], v[52:55]
	v_mfma_f32_16x16x32_bf16 v[48:51], v[210:213], v[168:171], v[48:51]
	v_mfma_f32_16x16x32_bf16 v[36:39], v[200:203], v[176:179], v[36:39]
	v_mfma_f32_16x16x32_bf16 v[32:35], v[210:213], v[176:179], v[32:35]
	v_mfma_f32_16x16x32_bf16 v[20:23], v[200:203], v[184:187], v[20:23]
	v_mfma_f32_16x16x32_bf16 v[16:19], v[210:213], v[184:187], v[16:19]
	v_mfma_f32_16x16x32_bf16 v[4:7], v[200:203], v[192:195], v[4:7]
	v_mfma_f32_16x16x32_bf16 v[0:3], v[210:213], v[192:195], v[0:3]
	v_mfma_f32_16x16x32_bf16 v[52:55], v[204:207], v[172:175], v[52:55]
	v_mfma_f32_16x16x32_bf16 v[48:51], v[214:217], v[172:175], v[48:51]
	v_mfma_f32_16x16x32_bf16 v[36:39], v[204:207], v[180:183], v[36:39]
	v_mfma_f32_16x16x32_bf16 v[32:35], v[214:217], v[180:183], v[32:35]
	v_mfma_f32_16x16x32_bf16 v[20:23], v[204:207], v[188:191], v[20:23]
	v_mfma_f32_16x16x32_bf16 v[16:19], v[214:217], v[188:191], v[16:19]
	v_mfma_f32_16x16x32_bf16 v[4:7], v[204:207], v[196:199], v[4:7]
	v_mfma_f32_16x16x32_bf16 v[0:3], v[214:217], v[196:199], v[0:3]
	s_setprio 0
	s_add_i32 s58, s58, 2
	s_add_u32 s56, s56, 0x100
	s_addc_u32 s57, s57, 0
	s_add_u32 s6, s6, 0x100
	s_addc_u32 s7, s7, 0
	s_cmp_gt_u32 s58, 29
	s_barrier
	s_cbranch_scc0 .LBB0_449
	v_lshl_add_u32 v156, s28, 8, v148
	v_ashrrev_i32_e32 v157, 31, v156
	v_lshl_add_u64 v[146:147], v[156:157], 2, s[8:9]
	global_load_dword v155, v[146:147], off
	global_load_dword v168, v[146:147], off offset:64
	global_load_dword v169, v[146:147], off offset:128
	global_load_dword v170, v[146:147], off offset:192
	global_load_dword v171, v[146:147], off offset:512
	global_load_dword v172, v[146:147], off offset:576
	global_load_dword v173, v[146:147], off offset:640
	global_load_dword v174, v[146:147], off offset:704
	v_lshl_or_b32 v144, s53, 8, v150
	v_ashrrev_i32_e32 v145, 31, v144
	v_lshlrev_b64 v[162:163], 1, v[144:145]
	v_lshlrev_b64 v[160:161], 14, v[156:157]
	v_or_b32_e32 v158, 16, v156
	v_ashrrev_i32_e32 v159, 31, v158
	s_mov_b32 s53, s20
	s_mov_b32 s28, s22
	s_mov_b64 s[30:31], s[26:27]
	s_mov_b64 s[34:35], s[24:25]
	s_waitcnt vmcnt(0)
	v_fmamk_f32 v144, v155, 0x3a000000, v154
	v_mul_f32_e32 v145, 0x4b800000, v144
	v_cmp_gt_f32_e32 vcc, s48, v144
	s_nop 1
	v_cndmask_b32_e32 v144, v144, v145, vcc
	v_rsq_f32_e32 v155, v144
	v_lshl_add_u64 v[144:145], s[94:95], 0, v[160:161]
	v_lshl_add_u64 v[144:145], v[144:145], 0, v[162:163]
	v_lshl_add_u64 v[160:161], v[158:159], 2, s[8:9]
	v_mul_f32_e32 v157, 0x45800000, v155
	v_cndmask_b32_e32 v164, v155, v157, vcc
	v_pk_mul_f32 v[126:127], v[126:127], v[164:165] op_sel_hi:[1,0]
	v_pk_mul_f32 v[124:125], v[124:125], v[164:165] op_sel_hi:[1,0]
	v_pk_mul_f32 v[122:123], v[122:123], v[164:165] op_sel_hi:[1,0]
	v_pk_mul_f32 v[120:121], v[120:121], v[164:165] op_sel_hi:[1,0]
	v_pk_mul_f32 v[118:119], v[118:119], v[164:165] op_sel_hi:[1,0]
	v_pk_mul_f32 v[116:117], v[116:117], v[164:165] op_sel_hi:[1,0]
	v_pk_mul_f32 v[166:167], v[114:115], v[164:165] op_sel_hi:[1,0]
	v_pk_mul_f32 v[164:165], v[112:113], v[164:165] op_sel_hi:[1,0]
	v_cvt_pk_bf16_f32 v112, v124, v125
	v_cvt_pk_bf16_f32 v113, v126, v127
	v_cvt_pk_bf16_f32 v114, v120, v121
	v_cvt_pk_bf16_f32 v115, v122, v123
	v_cvt_pk_bf16_f32 v116, v116, v117
	v_cvt_pk_bf16_f32 v117, v118, v119
	v_cvt_pk_bf16_f32 v118, v164, v165
	v_cvt_pk_bf16_f32 v119, v166, v167
	global_store_dwordx4 v[144:145], v[112:115], off
	global_store_dwordx4 v[144:145], v[116:119], off offset:256
	s_nop 1
	v_mov_b32_e32 v116, v168
	v_lshlrev_b64 v[114:115], 14, v[158:159]
	v_or_b32_e32 v112, 32, v156
	v_lshl_add_u64 v[114:115], s[94:95], 0, v[114:115]
	v_ashrrev_i32_e32 v113, 31, v112
	v_lshl_add_u64 v[114:115], v[114:115], 0, v[162:163]
	v_fmamk_f32 v116, v116, 0x3a000000, v154
	v_mul_f32_e32 v117, 0x4b800000, v116
	v_cmp_gt_f32_e32 vcc, s48, v116
	s_nop 1
	v_cndmask_b32_e32 v116, v116, v117, vcc
	v_rsq_f32_e32 v118, v116
	v_lshl_add_u64 v[116:117], v[112:113], 2, s[8:9]
	v_mul_f32_e32 v119, 0x45800000, v118
	v_cndmask_b32_e32 v118, v118, v119, vcc
	v_pk_mul_f32 v[110:111], v[110:111], v[118:119] op_sel_hi:[1,0]
; DI u32 pack2(float a, float b) { f32v2 v = {a, b}; return __builtin_bit_cast(u32, __builtin_convertvector(v, bf16v2)); }
;   DI void operator()(const f32x4 (&acc)[2][2][4][2], const Unit& u, int wr, int wc, int fr, int fq) const {
;     ...
;       for (int m = 0; m < 4; ++m) {
;         const int row = row0 + ai * HALF + m * 16;
;         u16* rowp = O + (size_t)row * ldc + col0;
;         const float rr = rs ? rsqrtf(rs[row] * (1.f / 2048.f) + 1e-6f) : 1.f;
; #pragma unroll
;         for (int bj = 0; bj < 2; ++bj) {
;           const f32x4 v0 = acc[ai][bj][m][0] * rr, v1 = acc[ai][bj][m][1] * rr;
;           u32x4 w = {pack2(v0[0], v0[1]), pack2(v0[2], v0[3]), pack2(v1[0], v1[1]), pack2(v1[2], v1[3])};
;           *reinterpret_cast<u32x4*>(rowp + bj * HALF) = w;
	v_pk_mul_f32 v[108:109], v[108:109], v[118:119] op_sel_hi:[1,0]
	v_pk_mul_f32 v[106:107], v[106:107], v[118:119] op_sel_hi:[1,0]
	v_pk_mul_f32 v[104:105], v[104:105], v[118:119] op_sel_hi:[1,0]
	v_pk_mul_f32 v[102:103], v[102:103], v[118:119] op_sel_hi:[1,0]
	v_pk_mul_f32 v[100:101], v[100:101], v[118:119] op_sel_hi:[1,0]
	v_pk_mul_f32 v[120:121], v[98:99], v[118:119] op_sel_hi:[1,0]
	v_pk_mul_f32 v[118:119], v[96:97], v[118:119] op_sel_hi:[1,0]
	v_cvt_pk_bf16_f32 v96, v108, v109
	v_cvt_pk_bf16_f32 v97, v110, v111
	v_cvt_pk_bf16_f32 v98, v104, v105
	v_cvt_pk_bf16_f32 v99, v106, v107
	v_cvt_pk_bf16_f32 v100, v100, v101
	v_cvt_pk_bf16_f32 v101, v102, v103
	v_cvt_pk_bf16_f32 v102, v118, v119
	v_cvt_pk_bf16_f32 v103, v120, v121
	global_store_dwordx4 v[114:115], v[96:99], off
	global_store_dwordx4 v[114:115], v[100:103], off offset:256
	s_nop 1
	v_mov_b32_e32 v100, v169
	v_lshlrev_b64 v[98:99], 14, v[112:113]
	v_or_b32_e32 v96, 48, v156
	v_lshl_add_u64 v[98:99], s[94:95], 0, v[98:99]
	v_ashrrev_i32_e32 v97, 31, v96
	v_lshl_add_u64 v[98:99], v[98:99], 0, v[162:163]
	v_fmamk_f32 v100, v100, 0x3a000000, v154
	v_mul_f32_e32 v101, 0x4b800000, v100
	v_cmp_gt_f32_e32 vcc, s48, v100
	s_nop 1
	v_cndmask_b32_e32 v100, v100, v101, vcc
	v_rsq_f32_e32 v102, v100
	v_lshl_add_u64 v[100:101], v[96:97], 2, s[8:9]
	v_mul_f32_e32 v103, 0x45800000, v102
	v_cndmask_b32_e32 v102, v102, v103, vcc
	v_pk_mul_f32 v[94:95], v[94:95], v[102:103] op_sel_hi:[1,0]
	v_pk_mul_f32 v[92:93], v[92:93], v[102:103] op_sel_hi:[1,0]
	v_pk_mul_f32 v[90:91], v[90:91], v[102:103] op_sel_hi:[1,0]
	v_pk_mul_f32 v[88:89], v[88:89], v[102:103] op_sel_hi:[1,0]
	v_pk_mul_f32 v[86:87], v[86:87], v[102:103] op_sel_hi:[1,0]
	v_pk_mul_f32 v[84:85], v[84:85], v[102:103] op_sel_hi:[1,0]
	v_pk_mul_f32 v[104:105], v[82:83], v[102:103] op_sel_hi:[1,0]
	v_pk_mul_f32 v[102:103], v[80:81], v[102:103] op_sel_hi:[1,0]
	v_cvt_pk_bf16_f32 v80, v92, v93
	v_cvt_pk_bf16_f32 v81, v94, v95
	v_cvt_pk_bf16_f32 v82, v88, v89
	v_cvt_pk_bf16_f32 v83, v90, v91
	v_cvt_pk_bf16_f32 v84, v84, v85
	v_cvt_pk_bf16_f32 v85, v86, v87
	v_cvt_pk_bf16_f32 v86, v102, v103
	v_cvt_pk_bf16_f32 v87, v104, v105
	global_store_dwordx4 v[98:99], v[80:83], off
	global_store_dwordx4 v[98:99], v[84:87], off offset:256
	s_nop 1
	v_mov_b32_e32 v80, v170
	v_fmamk_f32 v80, v80, 0x3a000000, v154
	v_mul_f32_e32 v81, 0x4b800000, v80
	v_cmp_gt_f32_e32 vcc, s48, v80
	s_nop 1
	v_cndmask_b32_e32 v80, v80, v81, vcc
	v_rsq_f32_e32 v82, v80
	v_lshlrev_b64 v[80:81], 14, v[96:97]
	v_lshl_add_u64 v[80:81], s[94:95], 0, v[80:81]
	v_lshl_add_u64 v[80:81], v[80:81], 0, v[162:163]
	v_mul_f32_e32 v83, 0x45800000, v82
	v_cndmask_b32_e32 v82, v82, v83, vcc
	v_pk_mul_f32 v[78:79], v[78:79], v[82:83] op_sel_hi:[1,0]
	v_pk_mul_f32 v[76:77], v[76:77], v[82:83] op_sel_hi:[1,0]
	v_pk_mul_f32 v[74:75], v[74:75], v[82:83] op_sel_hi:[1,0]
	v_pk_mul_f32 v[72:73], v[72:73], v[82:83] op_sel_hi:[1,0]
	v_pk_mul_f32 v[70:71], v[70:71], v[82:83] op_sel_hi:[1,0]
	v_pk_mul_f32 v[68:69], v[68:69], v[82:83] op_sel_hi:[1,0]
	v_pk_mul_f32 v[84:85], v[66:67], v[82:83] op_sel_hi:[1,0]
	v_pk_mul_f32 v[82:83], v[64:65], v[82:83] op_sel_hi:[1,0]
	v_cvt_pk_bf16_f32 v64, v76, v77
	v_cvt_pk_bf16_f32 v65, v78, v79
	v_cvt_pk_bf16_f32 v66, v72, v73
	v_cvt_pk_bf16_f32 v67, v74, v75
	v_cvt_pk_bf16_f32 v68, v68, v69
	v_cvt_pk_bf16_f32 v69, v70, v71
	v_cvt_pk_bf16_f32 v70, v82, v83
	v_cvt_pk_bf16_f32 v71, v84, v85
	global_store_dwordx4 v[80:81], v[64:67], off
	global_store_dwordx4 v[80:81], v[68:71], off offset:256
	s_nop 1
	v_mov_b32_e32 v66, v171
	v_lshl_add_u64 v[64:65], v[144:145], 0, s[12:13]
	v_fmamk_f32 v66, v66, 0x3a000000, v154
	v_mul_f32_e32 v67, 0x4b800000, v66
	v_cmp_gt_f32_e32 vcc, s48, v66
	s_nop 1
	v_cndmask_b32_e32 v66, v66, v67, vcc
	v_rsq_f32_e32 v68, v66
	v_add_co_u32_e64 v66, s[6:7], s49, v144
	v_mul_f32_e32 v69, 0x45800000, v68
	v_cndmask_b32_e32 v68, v68, v69, vcc
	v_pk_mul_f32 v[62:63], v[62:63], v[68:69] op_sel_hi:[1,0]
	v_pk_mul_f32 v[60:61], v[60:61], v[68:69] op_sel_hi:[1,0]
	v_pk_mul_f32 v[58:59], v[58:59], v[68:69] op_sel_hi:[1,0]
	v_pk_mul_f32 v[56:57], v[56:57], v[68:69] op_sel_hi:[1,0]
	v_addc_co_u32_e64 v67, s[6:7], 0, v145, s[6:7]
	v_pk_mul_f32 v[54:55], v[54:55], v[68:69] op_sel_hi:[1,0]
	v_pk_mul_f32 v[52:53], v[52:53], v[68:69] op_sel_hi:[1,0]
	v_pk_mul_f32 v[70:71], v[50:51], v[68:69] op_sel_hi:[1,0]
; DI u32 pack2(float a, float b) { f32v2 v = {a, b}; return __builtin_bit_cast(u32, __builtin_convertvector(v, bf16v2)); }
; #define PG8_WAIT_V(n) asm volatile("s_waitcnt vmcnt(" #n ")" ::: "memory")
; #define PG8_BAR __builtin_amdgcn_s_barrier()
; template <class Epi>
; DI void gemm_phase(LAS unsigned char* lds, const Gemm g, const StaticOrder& S, const Epi& E) {
;     ...
;   PG8_WAIT_V(0);
;   if (wr == 0) PG8_BAR;
;   PG8_BAR;
;   DI void operator()(const f32x4 (&acc)[2][2][4][2], const Unit& u, int wr, int wc, int fr, int fq) const {
;     ...
;       for (int m = 0; m < 4; ++m) {
;         const int row = row0 + ai * HALF + m * 16;
;         u16* rowp = O + (size_t)row * ldc + col0;
;         const float rr = rs ? rsqrtf(rs[row] * (1.f / 2048.f) + 1e-6f) : 1.f;
; #pragma unroll
;         for (int bj = 0; bj < 2; ++bj) {
;           const f32x4 v0 = acc[ai][bj][m][0] * rr, v1 = acc[ai][bj][m][1] * rr;
;           u32x4 w = {pack2(v0[0], v0[1]), pack2(v0[2], v0[3]), pack2(v1[0], v1[1]), pack2(v1[2], v1[3])};
;           *reinterpret_cast<u32x4*>(rowp + bj * HALF) = w;
	v_pk_mul_f32 v[68:69], v[48:49], v[68:69] op_sel_hi:[1,0]
	v_cvt_pk_bf16_f32 v48, v60, v61
	v_cvt_pk_bf16_f32 v49, v62, v63
	v_cvt_pk_bf16_f32 v50, v56, v57
	v_cvt_pk_bf16_f32 v51, v58, v59
	v_cvt_pk_bf16_f32 v52, v52, v53
	v_cvt_pk_bf16_f32 v53, v54, v55
	v_cvt_pk_bf16_f32 v54, v68, v69
	v_cvt_pk_bf16_f32 v55, v70, v71
	global_store_dwordx4 v[66:67], v[48:51], off
	global_store_dwordx4 v[64:65], v[52:55], off offset:256
	s_nop 1
	v_mov_b32_e32 v50, v172
	v_lshl_add_u64 v[48:49], v[144:145], 0, s[14:15]
	v_fmamk_f32 v50, v50, 0x3a000000, v154
	v_mul_f32_e32 v51, 0x4b800000, v50
	v_cmp_gt_f32_e32 vcc, s48, v50
	s_nop 1
	v_cndmask_b32_e32 v50, v50, v51, vcc
	v_rsq_f32_e32 v52, v50
	v_add_co_u32_e64 v50, s[6:7], s50, v144
	v_mul_f32_e32 v53, 0x45800000, v52
	v_cndmask_b32_e32 v52, v52, v53, vcc
	v_pk_mul_f32 v[46:47], v[46:47], v[52:53] op_sel_hi:[1,0]
	v_pk_mul_f32 v[44:45], v[44:45], v[52:53] op_sel_hi:[1,0]
	v_pk_mul_f32 v[42:43], v[42:43], v[52:53] op_sel_hi:[1,0]
	v_pk_mul_f32 v[40:41], v[40:41], v[52:53] op_sel_hi:[1,0]
	v_addc_co_u32_e64 v51, s[6:7], 0, v145, s[6:7]
	v_pk_mul_f32 v[38:39], v[38:39], v[52:53] op_sel_hi:[1,0]
	v_pk_mul_f32 v[36:37], v[36:37], v[52:53] op_sel_hi:[1,0]
	v_pk_mul_f32 v[54:55], v[34:35], v[52:53] op_sel_hi:[1,0]
	v_pk_mul_f32 v[52:53], v[32:33], v[52:53] op_sel_hi:[1,0]
	v_cvt_pk_bf16_f32 v32, v44, v45
	v_cvt_pk_bf16_f32 v33, v46, v47
	v_cvt_pk_bf16_f32 v34, v40, v41
	v_cvt_pk_bf16_f32 v35, v42, v43
	v_cvt_pk_bf16_f32 v36, v36, v37
	v_cvt_pk_bf16_f32 v37, v38, v39
	v_cvt_pk_bf16_f32 v38, v52, v53
	v_cvt_pk_bf16_f32 v39, v54, v55
	global_store_dwordx4 v[50:51], v[32:35], off
	global_store_dwordx4 v[48:49], v[36:39], off offset:256
	s_nop 1
	v_mov_b32_e32 v34, v173
	v_lshl_add_u64 v[32:33], v[144:145], 0, s[16:17]
	v_fmamk_f32 v34, v34, 0x3a000000, v154
	v_mul_f32_e32 v35, 0x4b800000, v34
	v_cmp_gt_f32_e32 vcc, s48, v34
	s_nop 1
	v_cndmask_b32_e32 v34, v34, v35, vcc
	v_rsq_f32_e32 v36, v34
	v_add_co_u32_e64 v34, s[6:7], s51, v144
	v_mul_f32_e32 v37, 0x45800000, v36
	v_cndmask_b32_e32 v36, v36, v37, vcc
	v_pk_mul_f32 v[30:31], v[30:31], v[36:37] op_sel_hi:[1,0]
	v_pk_mul_f32 v[28:29], v[28:29], v[36:37] op_sel_hi:[1,0]
	v_pk_mul_f32 v[26:27], v[26:27], v[36:37] op_sel_hi:[1,0]
	v_pk_mul_f32 v[24:25], v[24:25], v[36:37] op_sel_hi:[1,0]
	v_addc_co_u32_e64 v35, s[6:7], 0, v145, s[6:7]
	v_pk_mul_f32 v[22:23], v[22:23], v[36:37] op_sel_hi:[1,0]
	v_pk_mul_f32 v[20:21], v[20:21], v[36:37] op_sel_hi:[1,0]
	v_pk_mul_f32 v[38:39], v[18:19], v[36:37] op_sel_hi:[1,0]
	v_pk_mul_f32 v[36:37], v[16:17], v[36:37] op_sel_hi:[1,0]
	v_cvt_pk_bf16_f32 v16, v28, v29
	v_cvt_pk_bf16_f32 v17, v30, v31
	v_cvt_pk_bf16_f32 v18, v24, v25
	v_cvt_pk_bf16_f32 v19, v26, v27
	v_cvt_pk_bf16_f32 v20, v20, v21
	v_cvt_pk_bf16_f32 v21, v22, v23
	v_cvt_pk_bf16_f32 v22, v36, v37
	v_cvt_pk_bf16_f32 v23, v38, v39
	global_store_dwordx4 v[34:35], v[16:19], off
	global_store_dwordx4 v[32:33], v[20:23], off offset:256
	s_nop 1
	v_mov_b32_e32 v18, v174
	s_and_b64 vcc, exec, s[4:5]
	v_lshl_add_u64 v[16:17], v[144:145], 0, s[18:19]
	v_fmamk_f32 v18, v18, 0x3a000000, v154
	v_mul_f32_e32 v19, 0x4b800000, v18
	v_cmp_gt_f32_e64 s[4:5], s48, v18
	s_nop 1
	v_cndmask_b32_e64 v18, v18, v19, s[4:5]
	v_rsq_f32_e32 v20, v18
	v_add_co_u32_e64 v18, s[6:7], s52, v144
	v_mul_f32_e32 v21, 0x45800000, v20
	v_cndmask_b32_e64 v20, v20, v21, s[4:5]
	v_pk_mul_f32 v[14:15], v[14:15], v[20:21] op_sel_hi:[1,0]
	v_pk_mul_f32 v[12:13], v[12:13], v[20:21] op_sel_hi:[1,0]
	v_pk_mul_f32 v[10:11], v[10:11], v[20:21] op_sel_hi:[1,0]
	v_pk_mul_f32 v[8:9], v[8:9], v[20:21] op_sel_hi:[1,0]
	v_addc_co_u32_e64 v19, s[6:7], 0, v145, s[6:7]
	v_pk_mul_f32 v[6:7], v[6:7], v[20:21] op_sel_hi:[1,0]
	v_pk_mul_f32 v[4:5], v[4:5], v[20:21] op_sel_hi:[1,0]
	v_pk_mul_f32 v[22:23], v[2:3], v[20:21] op_sel_hi:[1,0]
	v_pk_mul_f32 v[20:21], v[0:1], v[20:21] op_sel_hi:[1,0]
	v_cvt_pk_bf16_f32 v0, v12, v13
	v_cvt_pk_bf16_f32 v1, v14, v15
	v_cvt_pk_bf16_f32 v2, v8, v9
	v_cvt_pk_bf16_f32 v3, v10, v11
	v_cvt_pk_bf16_f32 v4, v4, v5
	v_cvt_pk_bf16_f32 v5, v6, v7
	v_cvt_pk_bf16_f32 v6, v20, v21
	v_cvt_pk_bf16_f32 v7, v22, v23
	global_store_dwordx4 v[18:19], v[0:3], off
	global_store_dwordx4 v[16:17], v[4:7], off offset:256
	s_cbranch_vccz .LBB0_446
	s_waitcnt vmcnt(0)
	s_cmpk_gt_u32 s33, 0xff
	s_cbranch_scc1 .LBB0_453
	s_barrier

; #define PG8_STAGE(bufoff, gbase, voff) do { _Pragma("unroll") for (int _i = 0; _i < 2; ++_i) \
;     __builtin_amdgcn_global_load_lds((const unsigned*)((const char*)(gbase) + (voff)[_i]), (LAS unsigned*)(lds + (bufoff) + ldsw + _i * 8192), 16, 0, 0); } while (0)
; #define PG8_LDA(dst, b, h) do { _Pragma("unroll") for (int m = 0; m < 4; ++m) _Pragma("unroll") for (int k = 0; k < 2; ++k) dst[m][k] = *(const LAS bf16x8*)(lds + PG8_SA(b, h) + aoff + m * 2048 + k * 1024); } while (0)
; #define PG8_LDB(dst, b, h) do { _Pragma("unroll") for (int n = 0; n < 2; ++n) _Pragma("unroll") for (int k = 0; k < 2; ++k) dst[n][k] = *(const LAS bf16x8*)(lds + PG8_SB(b, h) + boff + n * 2048 + k * 1024); } while (0)
; #define PG8_MMA(ai, bj, At, Bt) do { __builtin_amdgcn_s_setprio(1); _Pragma("unroll") for (int m = 0; m < 4; ++m) _Pragma("unroll") for (int n = 0; n < 2; ++n) _Pragma("unroll") for (int k = 0; k < 2; ++k) \
;     acc[ai][bj][m][n] = __builtin_amdgcn_mfma_f32_16x16x32_bf16(Bt[n][k], At[m][k], acc[ai][bj][m][n], 0, 0, 0); __builtin_amdgcn_s_setprio(0); } while (0)
; #define PG8_WAIT_L(n) asm volatile("s_waitcnt lgkmcnt(" #n ")" ::: "memory")
; #define PG8_BAR __builtin_amdgcn_s_barrier()
; #define PG8_SCHED __builtin_amdgcn_sched_barrier(0)
; template <class Epi>
; DI void gemm_phase(LAS unsigned char* lds, const Gemm g, const StaticOrder& S, const Epi& E) {
;     ...
;       PG8_LDB(B0, 0, 0); PG8_SCHED; PG8_LDA(At, 0, 0); PG8_STAGE(PG8_SA(1, 1), a1 + hstep, voffA);
;       PG8_WAIT_L(8); PG8_BAR; PG8_WAIT_L(0); PG8_MMA(0, 0, At, B0); PG8_BAR; PG8_SCHED;
;       PG8_LDB(B1, 0, 1); PG8_STAGE(PG8_SB(0, 0), b2, voffB);
;       PG8_BAR; PG8_WAIT_L(0); PG8_MMA(0, 1, At, B1); PG8_BAR;
;       PG8_LDA(At, 0, 1); PG8_STAGE(PG8_SA(0, 0), a2, voffA);
;       PG8_BAR; PG8_WAIT_L(0); PG8_MMA(1, 0, At, B0); PG8_BAR; PG8_SCHED;
.LBB0_1239:
	ds_read_b128 v[144:147], v155
	ds_read_b128 v[148:151], v155 offset:1024
	ds_read_b128 v[160:163], v155 offset:2048
	ds_read_b128 v[164:167], v155 offset:3072
	s_add_u32 s24, s22, 0xfff80080
	s_addc_u32 s25, s23, -1
	s_cmp_eq_u32 s56, 28
	s_cselect_b32 s27, s15, s25
	s_cselect_b32 s26, s52, s24
	s_cselect_b32 s25, s13, s55
	s_cselect_b32 s24, s53, s54
	v_lshl_add_u64 v[200:201], s[22:23], 0, v[138:139]
	s_add_i32 m0, s21, 0xc000
	ds_read_b128 v[168:171], v156
	ds_read_b128 v[172:175], v156 offset:1024
	ds_read_b128 v[176:179], v156 offset:2048
	ds_read_b128 v[180:183], v156 offset:3072
	ds_read_b128 v[184:187], v156 offset:4096
	ds_read_b128 v[188:191], v156 offset:5120
	ds_read_b128 v[192:195], v156 offset:6144
	ds_read_b128 v[196:199], v156 offset:7168
	global_load_lds_dwordx4 v[200:201], off
	v_lshl_add_u64 v[200:201], s[22:23], 0, v[136:137]
	s_add_i32 m0, s21, 0xe000
	s_nop 0
	global_load_lds_dwordx4 v[200:201], off
	s_waitcnt lgkmcnt(8)
	s_barrier
	s_waitcnt lgkmcnt(0)
	s_setprio 1
	s_waitcnt lgkmcnt(0)
	v_mfma_f32_16x16x32_bf16 v[124:127], v[144:147], v[168:171], v[124:127]
	v_mfma_f32_16x16x32_bf16 v[120:123], v[160:163], v[168:171], v[120:123]
	v_mfma_f32_16x16x32_bf16 v[108:111], v[144:147], v[176:179], v[108:111]
	v_mfma_f32_16x16x32_bf16 v[104:107], v[160:163], v[176:179], v[104:107]
	v_mfma_f32_16x16x32_bf16 v[92:95], v[144:147], v[184:187], v[92:95]
	v_mfma_f32_16x16x32_bf16 v[88:91], v[160:163], v[184:187], v[88:91]
	v_mfma_f32_16x16x32_bf16 v[80:83], v[144:147], v[192:195], v[80:83]
	v_mfma_f32_16x16x32_bf16 v[72:75], v[160:163], v[192:195], v[72:75]
	v_mfma_f32_16x16x32_bf16 v[124:127], v[148:151], v[172:175], v[124:127]
	v_mfma_f32_16x16x32_bf16 v[120:123], v[164:167], v[172:175], v[120:123]
	v_mfma_f32_16x16x32_bf16 v[108:111], v[148:151], v[180:183], v[108:111]
	v_mfma_f32_16x16x32_bf16 v[104:107], v[164:167], v[180:183], v[104:107]
	v_mfma_f32_16x16x32_bf16 v[92:95], v[148:151], v[188:191], v[92:95]
	v_mfma_f32_16x16x32_bf16 v[88:91], v[164:167], v[188:191], v[88:91]
	v_mfma_f32_16x16x32_bf16 v[80:83], v[148:151], v[196:199], v[80:83]
	v_mfma_f32_16x16x32_bf16 v[72:75], v[164:167], v[196:199], v[72:75]
	s_setprio 0
	s_barrier
	s_add_i32 s57, s47, s30
	v_lshl_add_u64 v[218:219], s[24:25], 0, v[130:131]
	s_mov_b32 m0, s57
	ds_read_b128 v[200:203], v157
	ds_read_b128 v[204:207], v157 offset:1024
	ds_read_b128 v[210:213], v157 offset:2048
	ds_read_b128 v[214:217], v157 offset:3072
	global_load_lds_dwordx4 v[218:219], off
	v_lshl_add_u64 v[220:221], s[24:25], 0, v[134:135]
	s_add_i32 m0, s57, 0x2000
	s_nop 0
	global_load_lds_dwordx4 v[220:221], off
	s_barrier
	s_waitcnt lgkmcnt(0)
	s_setprio 1
	s_waitcnt lgkmcnt(0)
	v_mfma_f32_16x16x32_bf16 v[116:119], v[200:203], v[168:171], v[116:119]
	v_mfma_f32_16x16x32_bf16 v[112:115], v[210:213], v[168:171], v[112:115]
	v_mfma_f32_16x16x32_bf16 v[100:103], v[200:203], v[176:179], v[100:103]
	v_mfma_f32_16x16x32_bf16 v[96:99], v[210:213], v[176:179], v[96:99]
	v_mfma_f32_16x16x32_bf16 v[84:87], v[200:203], v[184:187], v[84:87]
	v_mfma_f32_16x16x32_bf16 v[76:79], v[210:213], v[184:187], v[76:79]
	v_mfma_f32_16x16x32_bf16 v[68:71], v[200:203], v[192:195], v[68:71]
	v_mfma_f32_16x16x32_bf16 v[64:67], v[210:213], v[192:195], v[64:67]
	v_mfma_f32_16x16x32_bf16 v[116:119], v[204:207], v[172:175], v[116:119]
	v_mfma_f32_16x16x32_bf16 v[112:115], v[214:217], v[172:175], v[112:115]
	v_mfma_f32_16x16x32_bf16 v[100:103], v[204:207], v[180:183], v[100:103]
	v_mfma_f32_16x16x32_bf16 v[96:99], v[214:217], v[180:183], v[96:99]
	v_mfma_f32_16x16x32_bf16 v[84:87], v[204:207], v[188:191], v[84:87]
	v_mfma_f32_16x16x32_bf16 v[76:79], v[214:217], v[188:191], v[76:79]
	v_mfma_f32_16x16x32_bf16 v[68:71], v[204:207], v[196:199], v[68:71]
	v_mfma_f32_16x16x32_bf16 v[64:67], v[214:217], v[196:199], v[64:67]
	s_setprio 0
	s_mov_b32 m0, s21
	v_lshl_add_u64 v[222:223], s[26:27], 0, v[128:129]
	s_barrier
	ds_read_b128 v[168:171], v156 offset:16384
	ds_read_b128 v[172:175], v156 offset:17408
	ds_read_b128 v[176:179], v156 offset:18432
	ds_read_b128 v[180:183], v156 offset:19456
	ds_read_b128 v[184:187], v156 offset:20480
	ds_read_b128 v[188:191], v156 offset:21504
	ds_read_b128 v[192:195], v156 offset:22528
	ds_read_b128 v[196:199], v156 offset:23552
	global_load_lds_dwordx4 v[222:223], off
	v_lshl_add_u64 v[224:225], s[26:27], 0, v[132:133]
	s_mov_b32 m0, s31
	s_nop 0
	global_load_lds_dwordx4 v[224:225], off
	s_barrier
	s_waitcnt lgkmcnt(0)
	s_setprio 1
	s_waitcnt lgkmcnt(0)
	v_mfma_f32_16x16x32_bf16 v[60:63], v[144:147], v[168:171], v[60:63]
	v_mfma_f32_16x16x32_bf16 v[56:59], v[160:163], v[168:171], v[56:59]
	v_mfma_f32_16x16x32_bf16 v[44:47], v[144:147], v[176:179], v[44:47]
	v_mfma_f32_16x16x32_bf16 v[40:43], v[160:163], v[176:179], v[40:43]
	v_mfma_f32_16x16x32_bf16 v[28:31], v[144:147], v[184:187], v[28:31]
	v_mfma_f32_16x16x32_bf16 v[24:27], v[160:163], v[184:187], v[24:27]
	v_mfma_f32_16x16x32_bf16 v[12:15], v[144:147], v[192:195], v[12:15]
	v_mfma_f32_16x16x32_bf16 v[8:11], v[160:163], v[192:195], v[8:11]
	v_mfma_f32_16x16x32_bf16 v[60:63], v[148:151], v[172:175], v[60:63]
	v_mfma_f32_16x16x32_bf16 v[56:59], v[164:167], v[172:175], v[56:59]
	v_mfma_f32_16x16x32_bf16 v[44:47], v[148:151], v[180:183], v[44:47]
	v_mfma_f32_16x16x32_bf16 v[40:43], v[164:167], v[180:183], v[40:43]
	v_mfma_f32_16x16x32_bf16 v[28:31], v[148:151], v[188:191], v[28:31]
	v_mfma_f32_16x16x32_bf16 v[24:27], v[164:167], v[188:191], v[24:27]
	v_mfma_f32_16x16x32_bf16 v[12:15], v[148:151], v[196:199], v[12:15]
	v_mfma_f32_16x16x32_bf16 v[8:11], v[164:167], v[196:199], v[8:11]
	s_setprio 0
	s_barrier
; #define PG8_STAGE(bufoff, gbase, voff) do { _Pragma("unroll") for (int _i = 0; _i < 2; ++_i) \
;     __builtin_amdgcn_global_load_lds((const unsigned*)((const char*)(gbase) + (voff)[_i]), (LAS unsigned*)(lds + (bufoff) + ldsw + _i * 8192), 16, 0, 0); } while (0)
; #define PG8_LDA(dst, b, h) do { _Pragma("unroll") for (int m = 0; m < 4; ++m) _Pragma("unroll") for (int k = 0; k < 2; ++k) dst[m][k] = *(const LAS bf16x8*)(lds + PG8_SA(b, h) + aoff + m * 2048 + k * 1024); } while (0)
; #define PG8_LDB(dst, b, h) do { _Pragma("unroll") for (int n = 0; n < 2; ++n) _Pragma("unroll") for (int k = 0; k < 2; ++k) dst[n][k] = *(const LAS bf16x8*)(lds + PG8_SB(b, h) + boff + n * 2048 + k * 1024); } while (0)
; #define PG8_MMA(ai, bj, At, Bt) do { __builtin_amdgcn_s_setprio(1); _Pragma("unroll") for (int m = 0; m < 4; ++m) _Pragma("unroll") for (int n = 0; n < 2; ++n) _Pragma("unroll") for (int k = 0; k < 2; ++k) \
;     acc[ai][bj][m][n] = __builtin_amdgcn_mfma_f32_16x16x32_bf16(Bt[n][k], At[m][k], acc[ai][bj][m][n], 0, 0, 0); __builtin_amdgcn_s_setprio(0); } while (0)
; #define PG8_WAIT_V(n) asm volatile("s_waitcnt vmcnt(" #n ")" ::: "memory")
; #define PG8_WAIT_L(n) asm volatile("s_waitcnt lgkmcnt(" #n ")" ::: "memory")
; #define PG8_BAR __builtin_amdgcn_s_barrier()
; #define PG8_SCHED __builtin_amdgcn_sched_barrier(0)
; template <class Epi>
; DI void gemm_phase(LAS unsigned char* lds, const Gemm g, const StaticOrder& S, const Epi& E) {
;     ...
;       PG8_STAGE(PG8_SB(0, 1), b2 + hstep, voffB);
;       PG8_WAIT_V(6); PG8_BAR; PG8_MMA(1, 1, At, B1); PG8_BAR;
;       PG8_LDB(B0, 1, 0); PG8_SCHED; PG8_LDA(At, 1, 0); PG8_STAGE(PG8_SA(0, 1), a2 + hstep, voffA);
;       PG8_WAIT_L(8); PG8_BAR; PG8_WAIT_L(0); PG8_MMA(0, 0, At, B0); PG8_BAR; PG8_SCHED;
;       PG8_LDB(B1, 1, 1); PG8_STAGE(PG8_SB(1, 0), b3, voffB);
;       PG8_BAR; PG8_WAIT_L(0); PG8_MMA(0, 1, At, B1); PG8_BAR;
;       PG8_LDA(At, 1, 1); PG8_STAGE(PG8_SA(1, 0), a3, voffA);
;       PG8_BAR; PG8_WAIT_L(0); PG8_MMA(1, 0, At, B0); PG8_BAR; PG8_SCHED;
	s_add_u32 s58, s24, 0x80000
	s_addc_u32 s59, s25, 0
	s_add_i32 s57, s48, s30
	v_lshl_add_u64 v[144:145], s[58:59], 0, v[130:131]
	s_mov_b32 m0, s57
	s_nop 0
	global_load_lds_dwordx4 v[144:145], off
	v_lshl_add_u64 v[144:145], s[58:59], 0, v[134:135]
	s_add_i32 m0, s57, 0x2000
	s_nop 0
	global_load_lds_dwordx4 v[144:145], off
	s_waitcnt vmcnt(6)
	s_barrier
	s_setprio 1
	v_mfma_f32_16x16x32_bf16 v[52:55], v[200:203], v[168:171], v[52:55]
	v_mfma_f32_16x16x32_bf16 v[48:51], v[210:213], v[168:171], v[48:51]
	v_mfma_f32_16x16x32_bf16 v[36:39], v[200:203], v[176:179], v[36:39]
	v_mfma_f32_16x16x32_bf16 v[32:35], v[210:213], v[176:179], v[32:35]
	v_mfma_f32_16x16x32_bf16 v[20:23], v[200:203], v[184:187], v[20:23]
	v_mfma_f32_16x16x32_bf16 v[16:19], v[210:213], v[184:187], v[16:19]
	v_mfma_f32_16x16x32_bf16 v[4:7], v[200:203], v[192:195], v[4:7]
	v_mfma_f32_16x16x32_bf16 v[0:3], v[210:213], v[192:195], v[0:3]
	v_mfma_f32_16x16x32_bf16 v[52:55], v[204:207], v[172:175], v[52:55]
	v_mfma_f32_16x16x32_bf16 v[48:51], v[214:217], v[172:175], v[48:51]
	v_mfma_f32_16x16x32_bf16 v[36:39], v[204:207], v[180:183], v[36:39]
	v_mfma_f32_16x16x32_bf16 v[32:35], v[214:217], v[180:183], v[32:35]
	v_mfma_f32_16x16x32_bf16 v[20:23], v[204:207], v[188:191], v[20:23]
	v_mfma_f32_16x16x32_bf16 v[16:19], v[214:217], v[188:191], v[16:19]
	v_mfma_f32_16x16x32_bf16 v[4:7], v[204:207], v[196:199], v[4:7]
	v_mfma_f32_16x16x32_bf16 v[0:3], v[214:217], v[196:199], v[0:3]
	s_setprio 0
	s_add_i32 s57, 0, 0x18000
	v_add_u32_e32 v159, s57, v153
	s_barrier
	ds_read_b128 v[144:147], v159
	ds_read_b128 v[148:151], v159 offset:1024
	ds_read_b128 v[160:163], v159 offset:2048
	ds_read_b128 v[164:167], v159 offset:3072
	s_add_u32 s26, s26, 0x80000
	s_addc_u32 s27, s27, 0
	s_mov_b32 m0, s33
	v_lshl_add_u64 v[200:201], s[26:27], 0, v[128:129]
	ds_read_b128 v[168:171], v156 offset:32768
	ds_read_b128 v[172:175], v156 offset:33792
	ds_read_b128 v[176:179], v156 offset:34816
	ds_read_b128 v[180:183], v156 offset:35840
	ds_read_b128 v[184:187], v156 offset:36864
	ds_read_b128 v[188:191], v156 offset:37888
	ds_read_b128 v[192:195], v156 offset:38912
	ds_read_b128 v[196:199], v156 offset:39936
	global_load_lds_dwordx4 v[200:201], off
	v_lshl_add_u64 v[200:201], s[26:27], 0, v[132:133]
	s_mov_b32 m0, s34
	s_nop 0
	global_load_lds_dwordx4 v[200:201], off
	s_waitcnt lgkmcnt(8)
	s_barrier
	s_waitcnt lgkmcnt(0)
	s_setprio 1
	s_waitcnt lgkmcnt(0)
	v_mfma_f32_16x16x32_bf16 v[124:127], v[144:147], v[168:171], v[124:127]
	v_mfma_f32_16x16x32_bf16 v[120:123], v[160:163], v[168:171], v[120:123]
	v_mfma_f32_16x16x32_bf16 v[108:111], v[144:147], v[176:179], v[108:111]
	v_mfma_f32_16x16x32_bf16 v[104:107], v[160:163], v[176:179], v[104:107]
	v_mfma_f32_16x16x32_bf16 v[92:95], v[144:147], v[184:187], v[92:95]
	v_mfma_f32_16x16x32_bf16 v[88:91], v[160:163], v[184:187], v[88:91]
	v_mfma_f32_16x16x32_bf16 v[80:83], v[144:147], v[192:195], v[80:83]
	v_mfma_f32_16x16x32_bf16 v[72:75], v[160:163], v[192:195], v[72:75]
	v_mfma_f32_16x16x32_bf16 v[124:127], v[148:151], v[172:175], v[124:127]
	v_mfma_f32_16x16x32_bf16 v[120:123], v[164:167], v[172:175], v[120:123]
	v_mfma_f32_16x16x32_bf16 v[108:111], v[148:151], v[180:183], v[108:111]
	v_mfma_f32_16x16x32_bf16 v[104:107], v[164:167], v[180:183], v[104:107]
	v_mfma_f32_16x16x32_bf16 v[92:95], v[148:151], v[188:191], v[92:95]
	v_mfma_f32_16x16x32_bf16 v[88:91], v[164:167], v[188:191], v[88:91]
	v_mfma_f32_16x16x32_bf16 v[80:83], v[148:151], v[196:199], v[80:83]
	v_mfma_f32_16x16x32_bf16 v[72:75], v[164:167], v[196:199], v[72:75]
	s_setprio 0
	s_barrier
	s_add_i32 s26, 0, 0x1c000
	s_add_i32 s27, s57, s30
	v_add_u32_e32 v159, s26, v153
	v_lshl_add_u64 v[218:219], v[218:219], 0, s[10:11]
	s_mov_b32 m0, s27
	ds_read_b128 v[200:203], v159
	ds_read_b128 v[204:207], v159 offset:1024
	ds_read_b128 v[210:213], v159 offset:2048
	ds_read_b128 v[214:217], v159 offset:3072
	global_load_lds_dwordx4 v[218:219], off
	v_lshl_add_u64 v[218:219], v[220:221], 0, s[10:11]
	s_add_i32 m0, s27, 0x2000
	s_nop 0
	global_load_lds_dwordx4 v[218:219], off
	s_barrier
	s_waitcnt lgkmcnt(0)
	s_setprio 1
	s_waitcnt lgkmcnt(0)
	v_mfma_f32_16x16x32_bf16 v[116:119], v[200:203], v[168:171], v[116:119]
	v_mfma_f32_16x16x32_bf16 v[112:115], v[210:213], v[168:171], v[112:115]
	v_mfma_f32_16x16x32_bf16 v[100:103], v[200:203], v[176:179], v[100:103]
	v_mfma_f32_16x16x32_bf16 v[96:99], v[210:213], v[176:179], v[96:99]
	v_mfma_f32_16x16x32_bf16 v[84:87], v[200:203], v[184:187], v[84:87]
	v_mfma_f32_16x16x32_bf16 v[76:79], v[210:213], v[184:187], v[76:79]
	v_mfma_f32_16x16x32_bf16 v[68:71], v[200:203], v[192:195], v[68:71]
	v_mfma_f32_16x16x32_bf16 v[64:67], v[210:213], v[192:195], v[64:67]
	v_mfma_f32_16x16x32_bf16 v[116:119], v[204:207], v[172:175], v[116:119]
	v_mfma_f32_16x16x32_bf16 v[112:115], v[214:217], v[172:175], v[112:115]
	v_mfma_f32_16x16x32_bf16 v[100:103], v[204:207], v[180:183], v[100:103]
	v_mfma_f32_16x16x32_bf16 v[96:99], v[214:217], v[180:183], v[96:99]
	v_mfma_f32_16x16x32_bf16 v[84:87], v[204:207], v[188:191], v[84:87]
	v_mfma_f32_16x16x32_bf16 v[76:79], v[214:217], v[188:191], v[76:79]
	v_mfma_f32_16x16x32_bf16 v[68:71], v[204:207], v[196:199], v[68:71]
	v_mfma_f32_16x16x32_bf16 v[64:67], v[214:217], v[196:199], v[64:67]
	s_setprio 0
	s_mov_b32 m0, s36
	v_lshl_add_u64 v[218:219], v[222:223], 0, s[10:11]
	s_barrier
	ds_read_b128 v[168:171], v156 offset:49152
	ds_read_b128 v[172:175], v156 offset:50176
	ds_read_b128 v[176:179], v156 offset:51200
	ds_read_b128 v[180:183], v156 offset:52224
	ds_read_b128 v[184:187], v156 offset:53248
	ds_read_b128 v[188:191], v156 offset:54272
	ds_read_b128 v[192:195], v156 offset:55296
	ds_read_b128 v[196:199], v156 offset:56320
	global_load_lds_dwordx4 v[218:219], off
	v_lshl_add_u64 v[218:219], v[224:225], 0, s[10:11]
	s_mov_b32 m0, s37
	s_nop 0
	global_load_lds_dwordx4 v[218:219], off
	s_barrier
; DI u32 pack2(float a, float b) { f32v2 v = {a, b}; return __builtin_bit_cast(u32, __builtin_convertvector(v, bf16v2)); }
; #define PG8_STAGE(bufoff, gbase, voff) do { _Pragma("unroll") for (int _i = 0; _i < 2; ++_i) \
;     __builtin_amdgcn_global_load_lds((const unsigned*)((const char*)(gbase) + (voff)[_i]), (LAS unsigned*)(lds + (bufoff) + ldsw + _i * 8192), 16, 0, 0); } while (0)
; #define PG8_LDA(dst, b, h) do { _Pragma("unroll") for (int m = 0; m < 4; ++m) _Pragma("unroll") for (int k = 0; k < 2; ++k) dst[m][k] = *(const LAS bf16x8*)(lds + PG8_SA(b, h) + aoff + m * 2048 + k * 1024); } while (0)
; #define PG8_MMA(ai, bj, At, Bt) do { __builtin_amdgcn_s_setprio(1); _Pragma("unroll") for (int m = 0; m < 4; ++m) _Pragma("unroll") for (int n = 0; n < 2; ++n) _Pragma("unroll") for (int k = 0; k < 2; ++k) \
;     acc[ai][bj][m][n] = __builtin_amdgcn_mfma_f32_16x16x32_bf16(Bt[n][k], At[m][k], acc[ai][bj][m][n], 0, 0, 0); __builtin_amdgcn_s_setprio(0); } while (0)
; #define PG8_BAR __builtin_amdgcn_s_barrier()
; template <class Epi>
; DI void gemm_phase(LAS unsigned char* lds, const Gemm g, const StaticOrder& S, const Epi& E) {
;     ...
;       PG8_BAR; PG8_WAIT_L(0); PG8_MMA(0, 1, At, B1); PG8_BAR;
;       PG8_LDA(At, 1, 1); PG8_STAGE(PG8_SA(1, 0), a3, voffA);
;       PG8_BAR; PG8_WAIT_L(0); PG8_MMA(1, 0, At, B0); PG8_BAR; PG8_SCHED;
;       PG8_STAGE(PG8_SB(1, 1), b3 + hstep, voffB);
;       PG8_WAIT_V(6); PG8_BAR; PG8_MMA(1, 1, At, B1); PG8_BAR;
;   DI void operator()(const f32x4 (&acc)[2][2][4][2], const Unit& u, int wr, int wc, int fr, int fq) const {
;     const int row0 = u.pm * BM + wr * 64 + fr, colt = u.pn * BM, col0 = colt + wc * 32 + 8 * fq;
;     const bool kv = (mode == 1) && colt >= 2048 && colt < 6144;
;     const int sec = colt >= 4096 ? 1 : 0;
; #pragma unroll
;     for (int ai = 0; ai < 2; ++ai)
; #pragma unroll
;       for (int m = 0; m < 4; ++m) {
;         const int row = row0 + ai * HALF + m * 16;
;         u16* rowp = O + (size_t)row * ldc + col0;
;         const float rr = rs ? rsqrtf(rs[row] * (1.f / 2048.f) + 1e-6f) : 1.f;
; #pragma unroll
;         for (int bj = 0; bj < 2; ++bj) {
;           const f32x4 v0 = acc[ai][bj][m][0] * rr, v1 = acc[ai][bj][m][1] * rr;
;           u32x4 w = {pack2(v0[0], v0[1]), pack2(v0[2], v0[3]), pack2(v1[0], v1[1]), pack2(v1[2], v1[3])};
;           *reinterpret_cast<u32x4*>(rowp + bj * HALF) = w;
	s_waitcnt lgkmcnt(0)
	s_setprio 1
	s_waitcnt lgkmcnt(0)
	v_mfma_f32_16x16x32_bf16 v[60:63], v[144:147], v[168:171], v[60:63]
	v_mfma_f32_16x16x32_bf16 v[56:59], v[160:163], v[168:171], v[56:59]
	v_mfma_f32_16x16x32_bf16 v[44:47], v[144:147], v[176:179], v[44:47]
	v_mfma_f32_16x16x32_bf16 v[40:43], v[160:163], v[176:179], v[40:43]
	v_mfma_f32_16x16x32_bf16 v[28:31], v[144:147], v[184:187], v[28:31]
	v_mfma_f32_16x16x32_bf16 v[24:27], v[160:163], v[184:187], v[24:27]
	v_mfma_f32_16x16x32_bf16 v[12:15], v[144:147], v[192:195], v[12:15]
	v_mfma_f32_16x16x32_bf16 v[8:11], v[160:163], v[192:195], v[8:11]
	v_mfma_f32_16x16x32_bf16 v[60:63], v[148:151], v[172:175], v[60:63]
	v_mfma_f32_16x16x32_bf16 v[56:59], v[164:167], v[172:175], v[56:59]
	v_mfma_f32_16x16x32_bf16 v[44:47], v[148:151], v[180:183], v[44:47]
	v_mfma_f32_16x16x32_bf16 v[40:43], v[164:167], v[180:183], v[40:43]
	v_mfma_f32_16x16x32_bf16 v[28:31], v[148:151], v[188:191], v[28:31]
	v_mfma_f32_16x16x32_bf16 v[24:27], v[164:167], v[188:191], v[24:27]
	v_mfma_f32_16x16x32_bf16 v[12:15], v[148:151], v[196:199], v[12:15]
	v_mfma_f32_16x16x32_bf16 v[8:11], v[164:167], v[196:199], v[8:11]
	s_setprio 0
	s_barrier
	s_add_u32 s24, s24, 0x80080
	s_addc_u32 s25, s25, 0
	s_add_i32 s26, s26, s30
	v_lshl_add_u64 v[144:145], s[24:25], 0, v[130:131]
	s_mov_b32 m0, s26
	s_nop 0
	global_load_lds_dwordx4 v[144:145], off
	v_lshl_add_u64 v[144:145], s[24:25], 0, v[134:135]
	s_add_i32 m0, s26, 0x2000
	s_nop 0
	global_load_lds_dwordx4 v[144:145], off
	s_waitcnt vmcnt(6)
	s_barrier
	s_setprio 1
	v_mfma_f32_16x16x32_bf16 v[52:55], v[200:203], v[168:171], v[52:55]
	v_mfma_f32_16x16x32_bf16 v[48:51], v[210:213], v[168:171], v[48:51]
	v_mfma_f32_16x16x32_bf16 v[36:39], v[200:203], v[176:179], v[36:39]
	v_mfma_f32_16x16x32_bf16 v[32:35], v[210:213], v[176:179], v[32:35]
	v_mfma_f32_16x16x32_bf16 v[20:23], v[200:203], v[184:187], v[20:23]
	v_mfma_f32_16x16x32_bf16 v[16:19], v[210:213], v[184:187], v[16:19]
	v_mfma_f32_16x16x32_bf16 v[4:7], v[200:203], v[192:195], v[4:7]
	v_mfma_f32_16x16x32_bf16 v[0:3], v[210:213], v[192:195], v[0:3]
	v_mfma_f32_16x16x32_bf16 v[52:55], v[204:207], v[172:175], v[52:55]
	v_mfma_f32_16x16x32_bf16 v[48:51], v[214:217], v[172:175], v[48:51]
	v_mfma_f32_16x16x32_bf16 v[36:39], v[204:207], v[180:183], v[36:39]
	v_mfma_f32_16x16x32_bf16 v[32:35], v[214:217], v[180:183], v[32:35]
	v_mfma_f32_16x16x32_bf16 v[20:23], v[204:207], v[188:191], v[20:23]
	v_mfma_f32_16x16x32_bf16 v[16:19], v[214:217], v[188:191], v[16:19]
	v_mfma_f32_16x16x32_bf16 v[4:7], v[204:207], v[196:199], v[4:7]
	v_mfma_f32_16x16x32_bf16 v[0:3], v[214:217], v[196:199], v[0:3]
	s_setprio 0
	s_add_i32 s56, s56, 2
	s_add_u32 s54, s54, 0x100
	s_addc_u32 s55, s55, 0
	s_add_u32 s22, s22, 0x100
	s_addc_u32 s23, s23, 0
	s_cmp_gt_u32 s56, 29
	s_barrier
	s_cbranch_scc0 .LBB0_1239
	v_lshl_add_u32 v144, s20, 8, v152
	v_ashrrev_i32_e32 v145, 31, v144
	v_lshl_add_u64 v[150:151], v[144:145], 2, s[8:9]
	global_load_dword v145, v[150:151], off
	global_load_dword v170, v[150:151], off offset:64
	global_load_dword v171, v[150:151], off offset:128
	global_load_dword v172, v[150:151], off offset:192
	global_load_dword v173, v[150:151], off offset:512
	global_load_dword v174, v[150:151], off offset:576
	global_load_dword v175, v[150:151], off offset:640
	global_load_dword v176, v[150:151], off offset:704
	v_lshl_or_b32 v148, s51, 8, v154
	v_mov_b64_e32 v[146:147], s[44:45]
	v_ashrrev_i32_e32 v149, 31, v148
	v_mad_i64_i32 v[160:161], s[22:23], v144, s49, v[146:147]
	v_or_b32_e32 v162, 16, v144
	v_lshlrev_b64 v[148:149], 1, v[148:149]
	v_ashrrev_i32_e32 v163, 31, v162
	v_lshl_add_u64 v[160:161], v[160:161], 0, v[148:149]
	v_lshl_add_u64 v[164:165], v[162:163], 2, s[8:9]
	s_mov_b64 s[24:25], s[16:17]
	s_mov_b32 s51, s12
	s_mov_b32 s20, s14
	s_waitcnt vmcnt(0)
	v_fmamk_f32 v145, v145, 0x3a000000, v158
	v_mul_f32_e32 v159, 0x4b800000, v145
	v_cmp_gt_f32_e32 vcc, s50, v145
	s_nop 1
	v_cndmask_b32_e32 v145, v145, v159, vcc
	v_rsq_f32_e32 v145, v145
	s_nop 0
	v_mul_f32_e32 v159, 0x45800000, v145
	v_cndmask_b32_e32 v166, v145, v159, vcc
	v_pk_mul_f32 v[126:127], v[126:127], v[166:167] op_sel_hi:[1,0]
	v_pk_mul_f32 v[124:125], v[124:125], v[166:167] op_sel_hi:[1,0]
	v_pk_mul_f32 v[122:123], v[122:123], v[166:167] op_sel_hi:[1,0]
	v_pk_mul_f32 v[120:121], v[120:121], v[166:167] op_sel_hi:[1,0]
	v_pk_mul_f32 v[118:119], v[118:119], v[166:167] op_sel_hi:[1,0]
	v_pk_mul_f32 v[116:117], v[116:117], v[166:167] op_sel_hi:[1,0]
	v_pk_mul_f32 v[168:169], v[114:115], v[166:167] op_sel_hi:[1,0]
	v_pk_mul_f32 v[166:167], v[112:113], v[166:167] op_sel_hi:[1,0]
	v_cvt_pk_bf16_f32 v112, v124, v125
	v_cvt_pk_bf16_f32 v113, v126, v127
	v_cvt_pk_bf16_f32 v114, v120, v121
	v_cvt_pk_bf16_f32 v115, v122, v123
	v_cvt_pk_bf16_f32 v116, v116, v117
	v_cvt_pk_bf16_f32 v117, v118, v119
	v_cvt_pk_bf16_f32 v118, v166, v167
	v_cvt_pk_bf16_f32 v119, v168, v169
	global_store_dwordx4 v[160:161], v[112:115], off
	global_store_dwordx4 v[160:161], v[116:119], off offset:256
	s_nop 1
	v_mov_b32_e32 v113, v170
	v_or_b32_e32 v112, 32, v144
	v_mad_i64_i32 v[114:115], s[22:23], v162, s49, v[146:147]
	v_lshl_add_u64 v[114:115], v[114:115], 0, v[148:149]
	v_fmamk_f32 v113, v113, 0x3a000000, v158
	v_mul_f32_e32 v116, 0x4b800000, v113
	v_cmp_gt_f32_e32 vcc, s50, v113
	s_nop 1
	v_cndmask_b32_e32 v113, v113, v116, vcc
	v_rsq_f32_e32 v118, v113
	v_ashrrev_i32_e32 v113, 31, v112
	v_lshl_add_u64 v[116:117], v[112:113], 2, s[8:9]
	v_mul_f32_e32 v113, 0x45800000, v118
	v_cndmask_b32_e32 v118, v118, v113, vcc
	v_pk_mul_f32 v[110:111], v[110:111], v[118:119] op_sel_hi:[1,0]
; DI u32 pack2(float a, float b) { f32v2 v = {a, b}; return __builtin_bit_cast(u32, __builtin_convertvector(v, bf16v2)); }
;   DI void operator()(const f32x4 (&acc)[2][2][4][2], const Unit& u, int wr, int wc, int fr, int fq) const {
;     ...
;       for (int m = 0; m < 4; ++m) {
;         const int row = row0 + ai * HALF + m * 16;
;         u16* rowp = O + (size_t)row * ldc + col0;
;         const float rr = rs ? rsqrtf(rs[row] * (1.f / 2048.f) + 1e-6f) : 1.f;
; #pragma unroll
;         for (int bj = 0; bj < 2; ++bj) {
;           const f32x4 v0 = acc[ai][bj][m][0] * rr, v1 = acc[ai][bj][m][1] * rr;
;           u32x4 w = {pack2(v0[0], v0[1]), pack2(v0[2], v0[3]), pack2(v1[0], v1[1]), pack2(v1[2], v1[3])};
;           *reinterpret_cast<u32x4*>(rowp + bj * HALF) = w;
	v_pk_mul_f32 v[108:109], v[108:109], v[118:119] op_sel_hi:[1,0]
	v_pk_mul_f32 v[106:107], v[106:107], v[118:119] op_sel_hi:[1,0]
	v_pk_mul_f32 v[104:105], v[104:105], v[118:119] op_sel_hi:[1,0]
	v_pk_mul_f32 v[102:103], v[102:103], v[118:119] op_sel_hi:[1,0]
	v_pk_mul_f32 v[100:101], v[100:101], v[118:119] op_sel_hi:[1,0]
	v_pk_mul_f32 v[120:121], v[98:99], v[118:119] op_sel_hi:[1,0]
	v_pk_mul_f32 v[118:119], v[96:97], v[118:119] op_sel_hi:[1,0]
	v_cvt_pk_bf16_f32 v96, v108, v109
	v_cvt_pk_bf16_f32 v97, v110, v111
	v_cvt_pk_bf16_f32 v98, v104, v105
	v_cvt_pk_bf16_f32 v99, v106, v107
	v_cvt_pk_bf16_f32 v100, v100, v101
	v_cvt_pk_bf16_f32 v101, v102, v103
	v_cvt_pk_bf16_f32 v102, v118, v119
	v_cvt_pk_bf16_f32 v103, v120, v121
	global_store_dwordx4 v[114:115], v[96:99], off
	global_store_dwordx4 v[114:115], v[100:103], off offset:256
	s_nop 1
	v_mov_b32_e32 v97, v171
	v_or_b32_e32 v96, 48, v144
	v_mad_i64_i32 v[98:99], s[22:23], v112, s49, v[146:147]
	v_lshl_add_u64 v[98:99], v[98:99], 0, v[148:149]
	v_fmamk_f32 v97, v97, 0x3a000000, v158
	v_mul_f32_e32 v100, 0x4b800000, v97
	v_cmp_gt_f32_e32 vcc, s50, v97
	s_nop 1
	v_cndmask_b32_e32 v97, v97, v100, vcc
	v_rsq_f32_e32 v102, v97
	v_ashrrev_i32_e32 v97, 31, v96
	v_lshl_add_u64 v[100:101], v[96:97], 2, s[8:9]
	v_mul_f32_e32 v97, 0x45800000, v102
	v_cndmask_b32_e32 v102, v102, v97, vcc
	v_pk_mul_f32 v[94:95], v[94:95], v[102:103] op_sel_hi:[1,0]
	v_pk_mul_f32 v[92:93], v[92:93], v[102:103] op_sel_hi:[1,0]
	v_pk_mul_f32 v[90:91], v[90:91], v[102:103] op_sel_hi:[1,0]
	v_pk_mul_f32 v[88:89], v[88:89], v[102:103] op_sel_hi:[1,0]
	v_pk_mul_f32 v[86:87], v[86:87], v[102:103] op_sel_hi:[1,0]
	v_pk_mul_f32 v[84:85], v[84:85], v[102:103] op_sel_hi:[1,0]
	v_pk_mul_f32 v[104:105], v[78:79], v[102:103] op_sel_hi:[1,0]
	v_pk_mul_f32 v[102:103], v[76:77], v[102:103] op_sel_hi:[1,0]
	v_cvt_pk_bf16_f32 v76, v92, v93
	v_cvt_pk_bf16_f32 v77, v94, v95
	v_cvt_pk_bf16_f32 v78, v88, v89
	v_cvt_pk_bf16_f32 v79, v90, v91
	v_cvt_pk_bf16_f32 v84, v84, v85
	v_cvt_pk_bf16_f32 v85, v86, v87
	v_cvt_pk_bf16_f32 v86, v102, v103
	v_cvt_pk_bf16_f32 v87, v104, v105
	global_store_dwordx4 v[98:99], v[76:79], off
	global_store_dwordx4 v[98:99], v[84:87], off offset:256
	s_nop 1
	v_mov_b32_e32 v76, v172
	v_fmamk_f32 v76, v76, 0x3a000000, v158
	v_mul_f32_e32 v77, 0x4b800000, v76
	v_cmp_gt_f32_e32 vcc, s50, v76
	s_nop 1
	v_cndmask_b32_e32 v76, v76, v77, vcc
	v_rsq_f32_e32 v78, v76
	v_mad_i64_i32 v[76:77], s[22:23], v96, s49, v[146:147]
	v_lshl_add_u64 v[76:77], v[76:77], 0, v[148:149]
	v_mul_f32_e32 v79, 0x45800000, v78
	v_cndmask_b32_e32 v78, v78, v79, vcc
	v_pk_mul_f32 v[82:83], v[82:83], v[78:79] op_sel_hi:[1,0]
	v_pk_mul_f32 v[80:81], v[80:81], v[78:79] op_sel_hi:[1,0]
	v_pk_mul_f32 v[74:75], v[74:75], v[78:79] op_sel_hi:[1,0]
	v_pk_mul_f32 v[72:73], v[72:73], v[78:79] op_sel_hi:[1,0]
	v_pk_mul_f32 v[70:71], v[70:71], v[78:79] op_sel_hi:[1,0]
	v_pk_mul_f32 v[68:69], v[68:69], v[78:79] op_sel_hi:[1,0]
	v_pk_mul_f32 v[84:85], v[66:67], v[78:79] op_sel_hi:[1,0]
	v_pk_mul_f32 v[78:79], v[64:65], v[78:79] op_sel_hi:[1,0]
	v_cvt_pk_bf16_f32 v64, v80, v81
	v_cvt_pk_bf16_f32 v65, v82, v83
	v_cvt_pk_bf16_f32 v66, v72, v73
	v_cvt_pk_bf16_f32 v67, v74, v75
	v_cvt_pk_bf16_f32 v68, v68, v69
	v_cvt_pk_bf16_f32 v69, v70, v71
	v_cvt_pk_bf16_f32 v70, v78, v79
	v_cvt_pk_bf16_f32 v71, v84, v85
	global_store_dwordx4 v[76:77], v[64:67], off
	global_store_dwordx4 v[76:77], v[68:71], off offset:256
	s_nop 1
	v_mov_b32_e32 v64, v173
	v_add_u32_e32 v65, 0x80, v144
	v_fmamk_f32 v64, v64, 0x3a000000, v158
	v_mul_f32_e32 v66, 0x4b800000, v64
	v_cmp_gt_f32_e32 vcc, s50, v64
	s_nop 1
	v_cndmask_b32_e32 v64, v64, v66, vcc
	v_rsq_f32_e32 v66, v64
	v_mad_i64_i32 v[64:65], s[22:23], v65, s49, v[146:147]
	v_lshl_add_u64 v[64:65], v[64:65], 0, v[148:149]
	v_mul_f32_e32 v67, 0x45800000, v66
	v_cndmask_b32_e32 v66, v66, v67, vcc
	v_pk_mul_f32 v[62:63], v[62:63], v[66:67] op_sel_hi:[1,0]
	v_pk_mul_f32 v[60:61], v[60:61], v[66:67] op_sel_hi:[1,0]
	v_pk_mul_f32 v[58:59], v[58:59], v[66:67] op_sel_hi:[1,0]
	v_pk_mul_f32 v[56:57], v[56:57], v[66:67] op_sel_hi:[1,0]
	v_pk_mul_f32 v[54:55], v[54:55], v[66:67] op_sel_hi:[1,0]
	v_pk_mul_f32 v[52:53], v[52:53], v[66:67] op_sel_hi:[1,0]
	v_pk_mul_f32 v[68:69], v[50:51], v[66:67] op_sel_hi:[1,0]
	v_pk_mul_f32 v[66:67], v[48:49], v[66:67] op_sel_hi:[1,0]
; DI u32 pack2(float a, float b) { f32v2 v = {a, b}; return __builtin_bit_cast(u32, __builtin_convertvector(v, bf16v2)); }
; #define PG8_WAIT_V(n) asm volatile("s_waitcnt vmcnt(" #n ")" ::: "memory")
; template <class Epi>
; DI void gemm_phase(LAS unsigned char* lds, const Gemm g, const StaticOrder& S, const Epi& E) {
;     ...
;     E(acc, cur, wr, wc, fr, fq);
;     if (!has_next) break;
; #pragma unroll
;     for (int a = 0; a < 2; ++a)
; #pragma unroll
;       for (int b = 0; b < 2; ++b)
; #pragma unroll
;         for (int m = 0; m < 4; ++m)
; #pragma unroll
;           for (int n = 0; n < 2; ++n) acc[a][b][m][n] = (f32x4){0.f, 0.f, 0.f, 0.f};
;     cur = nxt; cA = nA; cB = nB; ++ui;
;   }
;   PG8_WAIT_V(0);
;   DI void operator()(const f32x4 (&acc)[2][2][4][2], const Unit& u, int wr, int wc, int fr, int fq) const {
;     ...
;       for (int m = 0; m < 4; ++m) {
;         const int row = row0 + ai * HALF + m * 16;
;         u16* rowp = O + (size_t)row * ldc + col0;
;         const float rr = rs ? rsqrtf(rs[row] * (1.f / 2048.f) + 1e-6f) : 1.f;
; #pragma unroll
;         for (int bj = 0; bj < 2; ++bj) {
;           const f32x4 v0 = acc[ai][bj][m][0] * rr, v1 = acc[ai][bj][m][1] * rr;
;           u32x4 w = {pack2(v0[0], v0[1]), pack2(v0[2], v0[3]), pack2(v1[0], v1[1]), pack2(v1[2], v1[3])};
;           *reinterpret_cast<u32x4*>(rowp + bj * HALF) = w;
	v_cvt_pk_bf16_f32 v48, v60, v61
	v_cvt_pk_bf16_f32 v49, v62, v63
	v_cvt_pk_bf16_f32 v50, v56, v57
	v_cvt_pk_bf16_f32 v51, v58, v59
	v_cvt_pk_bf16_f32 v52, v52, v53
	v_cvt_pk_bf16_f32 v53, v54, v55
	v_cvt_pk_bf16_f32 v54, v66, v67
	v_cvt_pk_bf16_f32 v55, v68, v69
	global_store_dwordx4 v[64:65], v[48:51], off
	global_store_dwordx4 v[64:65], v[52:55], off offset:256
	s_nop 1
	v_mov_b32_e32 v48, v174
	v_add_u32_e32 v49, 0x90, v144
	v_fmamk_f32 v48, v48, 0x3a000000, v158
	v_mul_f32_e32 v50, 0x4b800000, v48
	v_cmp_gt_f32_e32 vcc, s50, v48
	s_nop 1
	v_cndmask_b32_e32 v48, v48, v50, vcc
	v_rsq_f32_e32 v50, v48
	v_mad_i64_i32 v[48:49], s[22:23], v49, s49, v[146:147]
	v_lshl_add_u64 v[48:49], v[48:49], 0, v[148:149]
	v_mul_f32_e32 v51, 0x45800000, v50
	v_cndmask_b32_e32 v50, v50, v51, vcc
	v_pk_mul_f32 v[46:47], v[46:47], v[50:51] op_sel_hi:[1,0]
	v_pk_mul_f32 v[44:45], v[44:45], v[50:51] op_sel_hi:[1,0]
	v_pk_mul_f32 v[42:43], v[42:43], v[50:51] op_sel_hi:[1,0]
	v_pk_mul_f32 v[40:41], v[40:41], v[50:51] op_sel_hi:[1,0]
	v_pk_mul_f32 v[38:39], v[38:39], v[50:51] op_sel_hi:[1,0]
	v_pk_mul_f32 v[36:37], v[36:37], v[50:51] op_sel_hi:[1,0]
	v_pk_mul_f32 v[52:53], v[34:35], v[50:51] op_sel_hi:[1,0]
	v_pk_mul_f32 v[50:51], v[32:33], v[50:51] op_sel_hi:[1,0]
	v_cvt_pk_bf16_f32 v32, v44, v45
	v_cvt_pk_bf16_f32 v33, v46, v47
	v_cvt_pk_bf16_f32 v34, v40, v41
	v_cvt_pk_bf16_f32 v35, v42, v43
	v_cvt_pk_bf16_f32 v36, v36, v37
	v_cvt_pk_bf16_f32 v37, v38, v39
	v_cvt_pk_bf16_f32 v38, v50, v51
	v_cvt_pk_bf16_f32 v39, v52, v53
	global_store_dwordx4 v[48:49], v[32:35], off
	global_store_dwordx4 v[48:49], v[36:39], off offset:256
	s_nop 1
	v_mov_b32_e32 v32, v175
	v_add_u32_e32 v33, 0xa0, v144
	v_fmamk_f32 v32, v32, 0x3a000000, v158
	v_mul_f32_e32 v34, 0x4b800000, v32
	v_cmp_gt_f32_e32 vcc, s50, v32
	s_nop 1
	v_cndmask_b32_e32 v32, v32, v34, vcc
	v_rsq_f32_e32 v34, v32
	v_mad_i64_i32 v[32:33], s[22:23], v33, s49, v[146:147]
	v_lshl_add_u64 v[32:33], v[32:33], 0, v[148:149]
	v_mul_f32_e32 v35, 0x45800000, v34
	v_cndmask_b32_e32 v34, v34, v35, vcc
	v_pk_mul_f32 v[30:31], v[30:31], v[34:35] op_sel_hi:[1,0]
	v_pk_mul_f32 v[28:29], v[28:29], v[34:35] op_sel_hi:[1,0]
	v_pk_mul_f32 v[26:27], v[26:27], v[34:35] op_sel_hi:[1,0]
	v_pk_mul_f32 v[24:25], v[24:25], v[34:35] op_sel_hi:[1,0]
	v_pk_mul_f32 v[22:23], v[22:23], v[34:35] op_sel_hi:[1,0]
	v_pk_mul_f32 v[20:21], v[20:21], v[34:35] op_sel_hi:[1,0]
	v_pk_mul_f32 v[36:37], v[18:19], v[34:35] op_sel_hi:[1,0]
	v_pk_mul_f32 v[34:35], v[16:17], v[34:35] op_sel_hi:[1,0]
	v_cvt_pk_bf16_f32 v16, v28, v29
	v_cvt_pk_bf16_f32 v17, v30, v31
	v_cvt_pk_bf16_f32 v18, v24, v25
	v_cvt_pk_bf16_f32 v19, v26, v27
	v_cvt_pk_bf16_f32 v20, v20, v21
	v_cvt_pk_bf16_f32 v21, v22, v23
	v_cvt_pk_bf16_f32 v22, v34, v35
	v_cvt_pk_bf16_f32 v23, v36, v37
	global_store_dwordx4 v[32:33], v[16:19], off
	global_store_dwordx4 v[32:33], v[20:23], off offset:256
	s_nop 1
	v_mov_b32_e32 v16, v176
	s_and_b64 vcc, exec, s[6:7]
	v_add_u32_e32 v17, 0xb0, v144
	s_mov_b64 s[22:23], s[18:19]
	v_fmamk_f32 v16, v16, 0x3a000000, v158
	v_mul_f32_e32 v18, 0x4b800000, v16
	v_cmp_gt_f32_e64 s[6:7], s50, v16
	s_nop 1
	v_cndmask_b32_e64 v16, v16, v18, s[6:7]
	v_rsq_f32_e32 v18, v16
	v_mad_i64_i32 v[16:17], s[16:17], v17, s49, v[146:147]
	v_lshl_add_u64 v[16:17], v[16:17], 0, v[148:149]
	v_mul_f32_e32 v19, 0x45800000, v18
	v_cndmask_b32_e64 v18, v18, v19, s[6:7]
	v_pk_mul_f32 v[14:15], v[14:15], v[18:19] op_sel_hi:[1,0]
	v_pk_mul_f32 v[12:13], v[12:13], v[18:19] op_sel_hi:[1,0]
	v_pk_mul_f32 v[10:11], v[10:11], v[18:19] op_sel_hi:[1,0]
	v_pk_mul_f32 v[8:9], v[8:9], v[18:19] op_sel_hi:[1,0]
	v_pk_mul_f32 v[6:7], v[6:7], v[18:19] op_sel_hi:[1,0]
	v_pk_mul_f32 v[4:5], v[4:5], v[18:19] op_sel_hi:[1,0]
	v_pk_mul_f32 v[20:21], v[2:3], v[18:19] op_sel_hi:[1,0]
	v_pk_mul_f32 v[18:19], v[0:1], v[18:19] op_sel_hi:[1,0]
	v_cvt_pk_bf16_f32 v0, v12, v13
	v_cvt_pk_bf16_f32 v1, v14, v15
	v_cvt_pk_bf16_f32 v2, v8, v9
	v_cvt_pk_bf16_f32 v3, v10, v11
	v_cvt_pk_bf16_f32 v4, v4, v5
	v_cvt_pk_bf16_f32 v5, v6, v7
	v_cvt_pk_bf16_f32 v6, v18, v19
	v_cvt_pk_bf16_f32 v7, v20, v21
	global_store_dwordx4 v[16:17], v[0:3], off
	global_store_dwordx4 v[16:17], v[4:7], off offset:256
	s_cbranch_vccz .LBB0_1232
	s_waitcnt vmcnt(0)
	s_cmpk_gt_u32 s4, 0xff
	s_cbranch_scc1 .LBB0_1243
	s_barrier
